# RG-LRU passes: log2(e) folded into the per-channel decay scale (sp = softplus * -8*log2 e once per unit), 512 fewer v_mul per thread; gr*sp goes straight to v_exp_f32
# baseline (speedup 1.0000x reference)
; __device__ __forceinline__ float softplus_(float x) { return x > 20.f ? x : log1pf(expf(x)); }
; template <int ph>
; __device__ __forceinline__ void run_phase(const Args& args, LAS unsigned char* lds, const int G, const int bx, const bool fin = true) {
;     ...
;             for (int unit = bx; unit < 128; unit += G) {
;                 const int b = unit >> 4, l8 = tid & 7, ch = (unit & 15) * 64 + 8 * l8, seg = tid >> 3, t0 = seg * 32;
;                 const f32x4 lam0 = *(const f32x4*)(lru_lambda + ch), lam1 = *(const f32x4*)(lru_lambda + ch + 4);
;                 const f32x4 sp0 = (f32x4){softplus_(-lam0[0]), softplus_(-lam0[1]), softplus_(-lam0[2]), softplus_(-lam0[3])} * -8.0f,
;                             sp1 = (f32x4){softplus_(-lam1[0]), softplus_(-lam1[1]), softplus_(-lam1[2]), softplus_(-lam1[3])} * -8.0f;
;                 const size_t base = ((size_t)b * T + t0) * D + ch;
;                 f32x4 A0 = (f32x4){1.f, 1.f, 1.f, 1.f}, A1 = A0, B0 = (f32x4){0.f, 0.f, 0.f, 0.f}, B1 = B0;
.LBB0_1041:
	s_cmpk_gt_i32 s81, 0x7f
	s_waitcnt vmcnt(0)
	s_barrier
	s_cbranch_scc1 .LBB0_1076
	v_ashrrev_i32_e32 v2, 3, v68
	v_lshlrev_b32_e32 v0, 5, v2
	v_readlane_b32 s8, v229, 48
	v_ashrrev_i32_e32 v1, 31, v0
	v_readlane_b32 s18, v229, 58
	v_readlane_b32 s19, v229, 59
	v_readlane_b32 s22, v229, 62
	v_readlane_b32 s23, v229, 63
	s_mov_b64 s[18:19], s[22:23]
	v_lshlrev_b64 v[0:1], 11, v[0:1]
	s_add_u32 s59, s18, 0x529a000
	v_and_b32_e32 v54, 7, v2
	v_lshl_add_u64 v[22:23], s[34:35], 0, v[0:1]
	v_lshlrev_b32_e32 v52, 3, v69
	v_lshl_add_u32 v53, v68, 5, 0
	v_cmp_lt_i32_e64 s[2:3], 0, v2
	v_cmp_eq_u32_e64 s[4:5], 63, v2
	s_addc_u32 s60, s19, 0
	v_cmp_lt_u32_e64 s[6:7], 7, v2
	v_and_b32_e32 v55, 0x7ffffff8, v2
	v_cmp_ne_u32_e64 s[30:31], 0, v54
	s_lshl_b32 s28, s81, 6
	s_lshl_b32 s29, s33, 6
	v_lshl_add_u32 v56, v69, 5, 0
	s_mov_b32 s38, 0xc1a00000
	s_mov_b32 s39, 0xbfb8aa3b
	s_mov_b32 s40, 0x42ce8ed0
	s_mov_b32 s41, 0xc2b17218
	s_mov_b32 s42, 0x7f800000
	s_mov_b32 s43, 0x3f2aaaab
	v_mov_b32_e32 v57, 0x3ecc95a3
	s_mov_b32 s44, 0x3f317218
	s_mov_b32 s45, 0x33800000
	s_mov_b32 s58, 0xc138aa3b
	s_mov_b32 s46, 0x10700000
	s_mov_b32 s47, 0x16a00000
	s_mov_b32 s48, 0x7d80000
	s_mov_b32 s49, 0xf800000
	v_mov_b32_e32 v58, 0x260
	s_mov_b32 s52, 0x10701000
	s_mov_b32 s53, 0x16a01000
	s_mov_b32 s54, 0x7d81000
	s_mov_b32 s55, 0x10702000
	s_mov_b32 s56, 0x16a02000
	s_mov_b32 s57, 0x7d82000
	s_mov_b32 s62, 0x10703000
	s_mov_b32 s63, 0x16a03000
	s_mov_b32 s74, 0x7d83000
	s_mov_b32 s75, 0x12801000
	s_mov_b32 s76, 0x12802000
	s_mov_b32 s77, 0x12803000
	v_mov_b32_e32 v59, 0x7f800000
	v_mov_b32_e32 v24, 0x3f317218
	v_mov_b32_e32 v0, 0
	s_mov_b32 s78, s81
	v_readlane_b32 s9, v229, 49
	v_readlane_b32 s10, v229, 50
	v_readlane_b32 s11, v229, 51
	v_readlane_b32 s12, v229, 52
	v_readlane_b32 s13, v229, 53
	v_readlane_b32 s14, v229, 54
	v_readlane_b32 s15, v229, 55
	v_readlane_b32 s16, v229, 56
	v_readlane_b32 s17, v229, 57
	v_readlane_b32 s20, v229, 60
	v_readlane_b32 s21, v229, 61
	s_branch .LBB0_1044

; __device__ __forceinline__ f32x4 unpack4(u32x2 u) { return (f32x4){__uint_as_float(u.x << 16), __uint_as_float(u.x & 0xffff0000u), __uint_as_float(u.y << 16), __uint_as_float(u.y & 0xffff0000u)}; }
; template <int ph>
; __device__ __forceinline__ void run_phase(const Args& args, LAS unsigned char* lds, const int G, const int bx, const bool fin = true) {
;     ...
;             auto lru_ab = [](f32x4 gr, f32x4 gi, f32x4 xc, f32x4 sp, f32x4& a, f32x4& bb) {
;                 const f32x4 la = gr * sp; a = (f32x4){__expf(la[0]), __expf(la[1]), __expf(la[2]), __expf(la[3])};
;                 const f32x4 om = (f32x4){1.f, 1.f, 1.f, 1.f} - a * a;
;                 bb = (f32x4){sqrtf(fmaxf(om[0], 0.f)), sqrtf(fmaxf(om[1], 0.f)), sqrtf(fmaxf(om[2], 0.f)), sqrtf(fmaxf(om[3], 0.f))} * gi * xc; };
;     ...
; #pragma unroll 8
;                 for (int t = 0; t < 32; ++t) { const size_t o = base + (size_t)t * D;
;                     const u32x4 gr = *(const u32x4*)(GR + o), gi = *(const u32x4*)(GI + o), xc = *(const u32x4*)(XC + o);
;                     f32x4 a, bb;
;                     lru_ab(unpack4((u32x2){gr.x, gr.y}), unpack4((u32x2){gi.x, gi.y}), unpack4((u32x2){xc.x, xc.y}), sp0, a, bb); A0 = A0 * a; B0 = a * B0 + bb;
;                     lru_ab(unpack4((u32x2){gr.z, gr.w}), unpack4((u32x2){gi.z, gi.w}), unpack4((u32x2){xc.z, xc.w}), sp1, a, bb); A1 = A1 * a; B1 = a * B1 + bb; }
.LBB0_1061:
	v_lshl_add_u64 v[18:19], v[34:35], 0, s[24:25]
	v_add_co_u32_e32 v176, vcc, s46, v18
	s_nop 1
	v_addc_co_u32_e32 v177, vcc, 0, v19, vcc
	v_add_co_u32_e32 v178, vcc, s52, v18
	s_nop 1
	v_addc_co_u32_e32 v179, vcc, 0, v19, vcc
	v_add_co_u32_e32 v180, vcc, s47, v18
	s_nop 1
	v_addc_co_u32_e32 v181, vcc, 0, v19, vcc
	v_add_co_u32_e32 v182, vcc, s53, v18
	s_nop 1
	v_addc_co_u32_e32 v183, vcc, 0, v19, vcc
	v_add_co_u32_e32 v184, vcc, s48, v18
	s_nop 1
	v_addc_co_u32_e32 v185, vcc, 0, v19, vcc
	v_add_co_u32_e32 v186, vcc, s54, v18
	s_nop 1
	v_addc_co_u32_e32 v187, vcc, 0, v19, vcc
	v_add_co_u32_e32 v188, vcc, s55, v18
	s_nop 1
	v_addc_co_u32_e32 v189, vcc, 0, v19, vcc
	v_add_co_u32_e32 v190, vcc, s62, v18
	s_nop 1
	v_addc_co_u32_e32 v191, vcc, 0, v19, vcc
	v_add_co_u32_e32 v192, vcc, s56, v18
	s_nop 1
	v_addc_co_u32_e32 v193, vcc, 0, v19, vcc
	v_add_co_u32_e32 v194, vcc, s63, v18
	s_nop 1
	v_addc_co_u32_e32 v195, vcc, 0, v19, vcc
	v_add_co_u32_e32 v196, vcc, s57, v18
	s_nop 1
	v_addc_co_u32_e32 v197, vcc, 0, v19, vcc
	v_add_co_u32_e32 v198, vcc, s74, v18
	s_nop 1
	v_addc_co_u32_e32 v199, vcc, 0, v19, vcc
	global_load_dwordx4 v[80:83], v[178:179], off offset:-4096
	global_load_dwordx4 v[84:87], v[182:183], off offset:-4096
	global_load_dwordx4 v[88:91], v[186:187], off offset:-4096
	global_load_dwordx4 v[92:95], v[176:177], off offset:2048
	global_load_dwordx4 v[96:99], v[180:181], off offset:2048
	global_load_dwordx4 v[100:103], v[184:185], off offset:2048
	global_load_dwordx4 v[104:107], v[178:179], off
	global_load_dwordx4 v[108:111], v[182:183], off
	global_load_dwordx4 v[112:115], v[186:187], off
	global_load_dwordx4 v[116:119], v[178:179], off offset:2048
	global_load_dwordx4 v[120:123], v[182:183], off offset:2048
	global_load_dwordx4 v[124:127], v[186:187], off offset:2048
	global_load_dwordx4 v[128:131], v[190:191], off offset:-4096
	global_load_dwordx4 v[132:135], v[194:195], off offset:-4096
	global_load_dwordx4 v[136:139], v[198:199], off offset:-4096
	global_load_dwordx4 v[140:143], v[188:189], off offset:2048
	global_load_dwordx4 v[144:147], v[192:193], off offset:2048
	global_load_dwordx4 v[148:151], v[196:197], off offset:2048
	global_load_dwordx4 v[152:155], v[190:191], off
	global_load_dwordx4 v[156:159], v[194:195], off
	global_load_dwordx4 v[160:163], v[198:199], off
	global_load_dwordx4 v[164:167], v[190:191], off offset:2048
	global_load_dwordx4 v[168:171], v[194:195], off offset:2048
	global_load_dwordx4 v[172:175], v[198:199], off offset:2048
	s_add_u32 s24, s24, 0x4000
	s_nop 0
	s_addc_u32 s25, s25, 0
	s_nop 0
	s_cmp_eq_u32 s24, 0x10000
	s_nop 0
	s_nop 1
	s_nop 0
	s_waitcnt vmcnt(23)
	v_lshlrev_b32_e32 v70, 16, v80
	v_and_b32_e32 v71, 0xffff0000, v80
	v_pk_mul_f32 v[70:71], v[28:29], v[70:71]
	v_lshlrev_b32_e32 v40, 16, v81
	v_exp_f32_e32 v70, v70
	v_exp_f32_e32 v71, v71
	v_and_b32_e32 v41, 0xffff0000, v81
	v_pk_mul_f32 v[40:41], v[26:27], v[40:41]
	v_exp_f32_e32 v40, v40
	v_pk_fma_f32 v[78:79], v[70:71], v[70:71], 1.0 op_sel_hi:[1,1,0] neg_lo:[1,0,0] neg_hi:[1,0,0]
	v_exp_f32_e32 v41, v41
	v_max_f32_e32 v1, 0, v78
	v_pk_fma_f32 v[76:77], v[40:41], v[40:41], 1.0 op_sel_hi:[1,1,0] neg_lo:[1,0,0] neg_hi:[1,0,0]
	s_waitcnt vmcnt(22)
	v_lshlrev_b32_e32 v72, 16, v84
	v_and_b32_e32 v73, 0xffff0000, v84
	v_lshlrev_b32_e32 v44, 16, v85
	v_and_b32_e32 v45, 0xffff0000, v85
	s_waitcnt vmcnt(21)
	v_lshlrev_b32_e32 v74, 16, v88
	v_sqrt_f32_e32 v78, v1
	v_max_f32_e32 v1, 0, v79
	v_and_b32_e32 v75, 0xffff0000, v88
	v_lshlrev_b32_e32 v48, 16, v89
	v_and_b32_e32 v49, 0xffff0000, v89
	v_sqrt_f32_e32 v79, v1
	v_max_f32_e32 v1, 0, v76
	v_pk_mul_f32 v[72:73], v[78:79], v[72:73]
	v_sqrt_f32_e32 v76, v1
	v_max_f32_e32 v1, 0, v77
	v_sqrt_f32_e32 v77, v1
	s_nop 0
	v_pk_mul_f32 v[44:45], v[76:77], v[44:45]
	s_nop 0
	v_pk_mul_f32 v[44:45], v[44:45], v[48:49]
	v_pk_mul_f32 v[48:49], v[72:73], v[74:75]
	v_pk_mul_f32 v[74:75], v[8:9], v[40:41]
	v_pk_fma_f32 v[48:49], v[2:3], v[70:71], v[48:49]
	v_lshlrev_b32_e32 v2, 16, v82
	v_and_b32_e32 v3, 0xffff0000, v82
	v_pk_mul_f32 v[2:3], v[32:33], v[2:3]
	v_pk_fma_f32 v[40:41], v[4:5], v[40:41], v[44:45]
	v_exp_f32_e32 v2, v2
	v_exp_f32_e32 v3, v3
	v_lshlrev_b32_e32 v4, 16, v83
	v_and_b32_e32 v5, 0xffff0000, v83
	v_pk_mul_f32 v[4:5], v[30:31], v[4:5]
	v_lshlrev_b32_e32 v42, 16, v90
	v_and_b32_e32 v43, 0xffff0000, v90
	v_lshlrev_b32_e32 v44, 16, v91
	v_and_b32_e32 v45, 0xffff0000, v91
	v_exp_f32_e32 v4, v4
	v_pk_fma_f32 v[50:51], v[2:3], v[2:3], 1.0 op_sel_hi:[1,1,0] neg_lo:[1,0,0] neg_hi:[1,0,0]
	v_exp_f32_e32 v5, v5
	v_max_f32_e32 v1, 0, v50
	v_pk_mul_f32 v[72:73], v[6:7], v[70:71]
	v_lshlrev_b32_e32 v6, 16, v86
	v_and_b32_e32 v7, 0xffff0000, v86
	v_lshlrev_b32_e32 v8, 16, v87
	v_and_b32_e32 v9, 0xffff0000, v87
	v_pk_fma_f32 v[46:47], v[4:5], v[4:5], 1.0 op_sel_hi:[1,1,0] neg_lo:[1,0,0] neg_hi:[1,0,0]
	s_nop 0
	v_sqrt_f32_e32 v50, v1
	v_max_f32_e32 v1, 0, v51
	v_sqrt_f32_e32 v51, v1
	v_max_f32_e32 v1, 0, v46
	v_pk_mul_f32 v[6:7], v[50:51], v[6:7]
	v_pk_mul_f32 v[6:7], v[6:7], v[42:43]
	v_pk_mul_f32 v[42:43], v[10:11], v[2:3]
	v_pk_fma_f32 v[14:15], v[14:15], v[2:3], v[6:7]
	v_sqrt_f32_e32 v46, v1
	v_max_f32_e32 v1, 0, v47
	v_sqrt_f32_e32 v47, v1
	s_nop 0
	v_pk_mul_f32 v[8:9], v[46:47], v[8:9]
	s_nop 0
	v_pk_mul_f32 v[8:9], v[8:9], v[44:45]
	v_pk_mul_f32 v[44:45], v[12:13], v[4:5]
	v_pk_fma_f32 v[16:17], v[16:17], v[4:5], v[8:9]
	s_waitcnt vmcnt(20)
; __device__ __forceinline__ f32x4 unpack4(u32x2 u) { return (f32x4){__uint_as_float(u.x << 16), __uint_as_float(u.x & 0xffff0000u), __uint_as_float(u.y << 16), __uint_as_float(u.y & 0xffff0000u)}; }
; template <int ph>
; __device__ __forceinline__ void run_phase(const Args& args, LAS unsigned char* lds, const int G, const int bx, const bool fin = true) {
;     ...
;             auto lru_ab = [](f32x4 gr, f32x4 gi, f32x4 xc, f32x4 sp, f32x4& a, f32x4& bb) {
;                 const f32x4 la = gr * sp; a = (f32x4){__expf(la[0]), __expf(la[1]), __expf(la[2]), __expf(la[3])};
;                 const f32x4 om = (f32x4){1.f, 1.f, 1.f, 1.f} - a * a;
;                 bb = (f32x4){sqrtf(fmaxf(om[0], 0.f)), sqrtf(fmaxf(om[1], 0.f)), sqrtf(fmaxf(om[2], 0.f)), sqrtf(fmaxf(om[3], 0.f))} * gi * xc; };
;     ...
; #pragma unroll 8
;                 for (int t = 0; t < 32; ++t) { const size_t o = base + (size_t)t * D;
;                     const u32x4 gr = *(const u32x4*)(GR + o), gi = *(const u32x4*)(GI + o), xc = *(const u32x4*)(XC + o);
;                     f32x4 a, bb;
;                     lru_ab(unpack4((u32x2){gr.x, gr.y}), unpack4((u32x2){gi.x, gi.y}), unpack4((u32x2){xc.x, xc.y}), sp0, a, bb); A0 = A0 * a; B0 = a * B0 + bb;
;                     lru_ab(unpack4((u32x2){gr.z, gr.w}), unpack4((u32x2){gi.z, gi.w}), unpack4((u32x2){xc.z, xc.w}), sp1, a, bb); A1 = A1 * a; B1 = a * B1 + bb; }
	v_lshlrev_b32_e32 v46, 16, v92
	v_and_b32_e32 v47, 0xffff0000, v92
	v_pk_mul_f32 v[46:47], v[28:29], v[46:47]
	v_lshlrev_b32_e32 v2, 16, v93
	v_exp_f32_e32 v46, v46
	v_exp_f32_e32 v47, v47
	v_and_b32_e32 v3, 0xffff0000, v93
	v_pk_mul_f32 v[2:3], v[26:27], v[2:3]
	v_exp_f32_e32 v2, v2
	v_pk_fma_f32 v[66:67], v[46:47], v[46:47], 1.0 op_sel_hi:[1,1,0] neg_lo:[1,0,0] neg_hi:[1,0,0]
	v_exp_f32_e32 v3, v3
	v_max_f32_e32 v1, 0, v66
	v_pk_fma_f32 v[64:65], v[2:3], v[2:3], 1.0 op_sel_hi:[1,1,0] neg_lo:[1,0,0] neg_hi:[1,0,0]
	s_waitcnt vmcnt(19)
	v_lshlrev_b32_e32 v50, 16, v96
	v_and_b32_e32 v51, 0xffff0000, v96
	v_lshlrev_b32_e32 v6, 16, v97
	v_and_b32_e32 v7, 0xffff0000, v97
	s_waitcnt vmcnt(18)
	v_lshlrev_b32_e32 v62, 16, v100
	v_and_b32_e32 v63, 0xffff0000, v100
	v_sqrt_f32_e32 v66, v1
	v_max_f32_e32 v1, 0, v67
	v_lshlrev_b32_e32 v10, 16, v101
	v_and_b32_e32 v11, 0xffff0000, v101
	v_sqrt_f32_e32 v67, v1
	v_max_f32_e32 v1, 0, v64
	v_pk_mul_f32 v[50:51], v[66:67], v[50:51]
	v_pk_mul_f32 v[50:51], v[50:51], v[62:63]
	v_pk_mul_f32 v[62:63], v[74:75], v[2:3]
	v_sqrt_f32_e32 v64, v1
	v_max_f32_e32 v1, 0, v65
	v_sqrt_f32_e32 v65, v1
	s_nop 0
	v_pk_mul_f32 v[6:7], v[64:65], v[6:7]
	v_pk_mul_f32 v[64:65], v[72:73], v[46:47]
	v_pk_mul_f32 v[6:7], v[6:7], v[10:11]
	v_pk_fma_f32 v[46:47], v[48:49], v[46:47], v[50:51]
	v_pk_fma_f32 v[40:41], v[40:41], v[2:3], v[6:7]
	v_lshlrev_b32_e32 v2, 16, v94
	v_and_b32_e32 v3, 0xffff0000, v94
	v_pk_mul_f32 v[2:3], v[32:33], v[2:3]
	v_lshlrev_b32_e32 v4, 16, v95
	v_exp_f32_e32 v2, v2
	v_exp_f32_e32 v3, v3
	v_and_b32_e32 v5, 0xffff0000, v95
	v_pk_mul_f32 v[4:5], v[30:31], v[4:5]
	v_exp_f32_e32 v4, v4
	v_pk_fma_f32 v[50:51], v[2:3], v[2:3], 1.0 op_sel_hi:[1,1,0] neg_lo:[1,0,0] neg_hi:[1,0,0]
	v_exp_f32_e32 v5, v5
	v_max_f32_e32 v1, 0, v50
	v_pk_fma_f32 v[48:49], v[4:5], v[4:5], 1.0 op_sel_hi:[1,1,0] neg_lo:[1,0,0] neg_hi:[1,0,0]
	v_lshlrev_b32_e32 v6, 16, v98
	v_and_b32_e32 v7, 0xffff0000, v98
	v_lshlrev_b32_e32 v8, 16, v99
	v_and_b32_e32 v9, 0xffff0000, v99
	v_lshlrev_b32_e32 v10, 16, v102
	v_and_b32_e32 v11, 0xffff0000, v102
	v_sqrt_f32_e32 v50, v1
	v_max_f32_e32 v1, 0, v51
	v_lshlrev_b32_e32 v12, 16, v103
	v_and_b32_e32 v13, 0xffff0000, v103
	v_pk_mul_f32 v[44:45], v[44:45], v[4:5]
	v_pk_mul_f32 v[42:43], v[42:43], v[2:3]
	v_sqrt_f32_e32 v51, v1
	v_max_f32_e32 v1, 0, v48
	v_pk_mul_f32 v[6:7], v[50:51], v[6:7]
	v_pk_mul_f32 v[6:7], v[6:7], v[10:11]
	v_pk_fma_f32 v[14:15], v[14:15], v[2:3], v[6:7]
	v_sqrt_f32_e32 v48, v1
	v_max_f32_e32 v1, 0, v49
	v_sqrt_f32_e32 v49, v1
	s_nop 0
	v_pk_mul_f32 v[8:9], v[48:49], v[8:9]
	s_nop 0
	v_pk_mul_f32 v[8:9], v[8:9], v[12:13]
	s_nop 0
	v_pk_fma_f32 v[16:17], v[16:17], v[4:5], v[8:9]
	s_waitcnt vmcnt(17)
	v_lshlrev_b32_e32 v48, 16, v104
	v_and_b32_e32 v49, 0xffff0000, v104
	v_pk_mul_f32 v[48:49], v[28:29], v[48:49]
	v_lshlrev_b32_e32 v2, 16, v105
	v_exp_f32_e32 v48, v48
	v_exp_f32_e32 v49, v49
	v_and_b32_e32 v3, 0xffff0000, v105
	v_pk_mul_f32 v[2:3], v[26:27], v[2:3]
	v_exp_f32_e32 v2, v2
	v_pk_fma_f32 v[72:73], v[48:49], v[48:49], 1.0 op_sel_hi:[1,1,0] neg_lo:[1,0,0] neg_hi:[1,0,0]
	v_exp_f32_e32 v3, v3
	v_max_f32_e32 v1, 0, v72
	v_pk_fma_f32 v[70:71], v[2:3], v[2:3], 1.0 op_sel_hi:[1,1,0] neg_lo:[1,0,0] neg_hi:[1,0,0]
	s_waitcnt vmcnt(16)
	v_lshlrev_b32_e32 v50, 16, v108
	v_and_b32_e32 v51, 0xffff0000, v108
	v_lshlrev_b32_e32 v6, 16, v109
	v_and_b32_e32 v7, 0xffff0000, v109
	s_waitcnt vmcnt(15)
	v_lshlrev_b32_e32 v66, 16, v112
	v_and_b32_e32 v67, 0xffff0000, v112
	v_sqrt_f32_e32 v72, v1
	v_max_f32_e32 v1, 0, v73
	v_lshlrev_b32_e32 v10, 16, v113
	v_and_b32_e32 v11, 0xffff0000, v113
	v_pk_mul_f32 v[62:63], v[62:63], v[2:3]
	v_sqrt_f32_e32 v73, v1
	v_max_f32_e32 v1, 0, v70
	v_pk_mul_f32 v[50:51], v[72:73], v[50:51]
	v_sqrt_f32_e32 v70, v1
	v_max_f32_e32 v1, 0, v71
	v_sqrt_f32_e32 v71, v1
	s_nop 0
	v_pk_mul_f32 v[6:7], v[70:71], v[6:7]
	s_nop 0
	v_pk_mul_f32 v[6:7], v[6:7], v[10:11]
	v_pk_mul_f32 v[10:11], v[50:51], v[66:67]
	v_pk_fma_f32 v[40:41], v[40:41], v[2:3], v[6:7]
	v_lshlrev_b32_e32 v2, 16, v106
	v_and_b32_e32 v3, 0xffff0000, v106
	v_pk_mul_f32 v[2:3], v[32:33], v[2:3]
	v_lshlrev_b32_e32 v4, 16, v107
	v_exp_f32_e32 v2, v2
	v_exp_f32_e32 v3, v3
	v_and_b32_e32 v5, 0xffff0000, v107
	v_pk_mul_f32 v[4:5], v[30:31], v[4:5]
	v_pk_mul_f32 v[50:51], v[64:65], v[48:49]
	v_exp_f32_e32 v4, v4
	v_pk_fma_f32 v[64:65], v[2:3], v[2:3], 1.0 op_sel_hi:[1,1,0] neg_lo:[1,0,0] neg_hi:[1,0,0]
	v_exp_f32_e32 v5, v5
	v_max_f32_e32 v1, 0, v64
	v_pk_fma_f32 v[46:47], v[46:47], v[48:49], v[10:11]
	v_pk_fma_f32 v[48:49], v[4:5], v[4:5], 1.0 op_sel_hi:[1,1,0] neg_lo:[1,0,0] neg_hi:[1,0,0]
	v_lshlrev_b32_e32 v6, 16, v110
	v_and_b32_e32 v7, 0xffff0000, v110
	v_lshlrev_b32_e32 v8, 16, v111
	v_and_b32_e32 v9, 0xffff0000, v111
	v_lshlrev_b32_e32 v10, 16, v114
	v_sqrt_f32_e32 v64, v1
	v_max_f32_e32 v1, 0, v65
	v_and_b32_e32 v11, 0xffff0000, v114
	v_lshlrev_b32_e32 v12, 16, v115
	v_and_b32_e32 v13, 0xffff0000, v115
	v_pk_mul_f32 v[44:45], v[44:45], v[4:5]
	v_pk_mul_f32 v[42:43], v[42:43], v[2:3]
	v_sqrt_f32_e32 v65, v1
	v_max_f32_e32 v1, 0, v48
	v_pk_mul_f32 v[6:7], v[64:65], v[6:7]
	v_pk_mul_f32 v[6:7], v[6:7], v[10:11]
	v_sqrt_f32_e32 v48, v1
	v_max_f32_e32 v1, 0, v49
	v_sqrt_f32_e32 v49, v1
	s_nop 0
	v_pk_mul_f32 v[8:9], v[48:49], v[8:9]
	v_pk_fma_f32 v[48:49], v[14:15], v[2:3], v[6:7]
	v_pk_mul_f32 v[8:9], v[8:9], v[12:13]
	s_nop 0
	v_pk_fma_f32 v[8:9], v[16:17], v[4:5], v[8:9]
	s_nop 0
	s_waitcnt vmcnt(14)
	v_lshlrev_b32_e32 v2, 16, v116
	v_and_b32_e32 v3, 0xffff0000, v116
	v_pk_mul_f32 v[2:3], v[28:29], v[2:3]
	s_waitcnt vmcnt(12)
; __device__ __forceinline__ f32x4 unpack4(u32x2 u) { return (f32x4){__uint_as_float(u.x << 16), __uint_as_float(u.x & 0xffff0000u), __uint_as_float(u.y << 16), __uint_as_float(u.y & 0xffff0000u)}; }
; template <int ph>
; __device__ __forceinline__ void run_phase(const Args& args, LAS unsigned char* lds, const int G, const int bx, const bool fin = true) {
;     ...
;             auto lru_ab = [](f32x4 gr, f32x4 gi, f32x4 xc, f32x4 sp, f32x4& a, f32x4& bb) {
;                 const f32x4 la = gr * sp; a = (f32x4){__expf(la[0]), __expf(la[1]), __expf(la[2]), __expf(la[3])};
;                 const f32x4 om = (f32x4){1.f, 1.f, 1.f, 1.f} - a * a;
;                 bb = (f32x4){sqrtf(fmaxf(om[0], 0.f)), sqrtf(fmaxf(om[1], 0.f)), sqrtf(fmaxf(om[2], 0.f)), sqrtf(fmaxf(om[3], 0.f))} * gi * xc; };
;     ...
; #pragma unroll 8
;                 for (int t = 0; t < 32; ++t) { const size_t o = base + (size_t)t * D;
;                     const u32x4 gr = *(const u32x4*)(GR + o), gi = *(const u32x4*)(GI + o), xc = *(const u32x4*)(XC + o);
;                     f32x4 a, bb;
;                     lru_ab(unpack4((u32x2){gr.x, gr.y}), unpack4((u32x2){gi.x, gi.y}), unpack4((u32x2){xc.x, xc.y}), sp0, a, bb); A0 = A0 * a; B0 = a * B0 + bb;
;                     lru_ab(unpack4((u32x2){gr.z, gr.w}), unpack4((u32x2){gi.z, gi.w}), unpack4((u32x2){xc.z, xc.w}), sp1, a, bb); A1 = A1 * a; B1 = a * B1 + bb; }
	v_lshlrev_b32_e32 v16, 16, v124
	v_and_b32_e32 v17, 0xffff0000, v124
	v_exp_f32_e32 v36, v2
	v_lshlrev_b32_e32 v20, 16, v125
	v_and_b32_e32 v21, 0xffff0000, v125
	v_exp_f32_e32 v37, v3
	v_lshlrev_b32_e32 v4, 16, v117
	v_and_b32_e32 v5, 0xffff0000, v117
	v_pk_mul_f32 v[4:5], v[26:27], v[4:5]
	v_exp_f32_e32 v4, v4
	v_pk_fma_f32 v[64:65], v[36:37], v[36:37], 1.0 op_sel_hi:[1,1,0] neg_lo:[1,0,0] neg_hi:[1,0,0]
	v_exp_f32_e32 v5, v5
	v_max_f32_e32 v1, 0, v64
	v_pk_fma_f32 v[2:3], v[4:5], v[4:5], 1.0 op_sel_hi:[1,1,0] neg_lo:[1,0,0] neg_hi:[1,0,0]
	v_lshlrev_b32_e32 v10, 16, v120
	v_and_b32_e32 v11, 0xffff0000, v120
	v_lshlrev_b32_e32 v12, 16, v121
	v_and_b32_e32 v13, 0xffff0000, v121
	v_sqrt_f32_e32 v64, v1
	v_max_f32_e32 v1, 0, v65
	v_sqrt_f32_e32 v65, v1
	v_max_f32_e32 v1, 0, v2
	v_pk_mul_f32 v[10:11], v[64:65], v[10:11]
	v_sqrt_f32_e32 v2, v1
	v_max_f32_e32 v1, 0, v3
	v_sqrt_f32_e32 v3, v1
	s_nop 0
	v_pk_mul_f32 v[2:3], v[2:3], v[12:13]
	v_pk_mul_f32 v[12:13], v[10:11], v[16:17]
	v_pk_mul_f32 v[16:17], v[2:3], v[20:21]
	v_pk_mul_f32 v[2:3], v[62:63], v[4:5]
	v_pk_fma_f32 v[4:5], v[40:41], v[4:5], v[16:17]
	v_lshlrev_b32_e32 v16, 16, v118
	v_and_b32_e32 v17, 0xffff0000, v118
	v_pk_mul_f32 v[16:17], v[32:33], v[16:17]
	v_lshlrev_b32_e32 v6, 16, v119
	v_exp_f32_e32 v16, v16
	v_exp_f32_e32 v17, v17
	v_and_b32_e32 v7, 0xffff0000, v119
	v_pk_mul_f32 v[6:7], v[30:31], v[6:7]
	v_pk_fma_f32 v[12:13], v[46:47], v[36:37], v[12:13]
	v_exp_f32_e32 v40, v6
	v_pk_fma_f32 v[46:47], v[16:17], v[16:17], 1.0 op_sel_hi:[1,1,0] neg_lo:[1,0,0] neg_hi:[1,0,0]
	v_exp_f32_e32 v41, v7
	v_max_f32_e32 v1, 0, v46
	v_pk_mul_f32 v[10:11], v[50:51], v[36:37]
	v_pk_fma_f32 v[6:7], v[40:41], v[40:41], 1.0 op_sel_hi:[1,1,0] neg_lo:[1,0,0] neg_hi:[1,0,0]
	v_lshlrev_b32_e32 v20, 16, v122
	v_and_b32_e32 v21, 0xffff0000, v122
	v_lshlrev_b32_e32 v14, 16, v123
	v_and_b32_e32 v15, 0xffff0000, v123
	v_lshlrev_b32_e32 v36, 16, v126
	v_sqrt_f32_e32 v46, v1
	v_max_f32_e32 v1, 0, v47
	v_and_b32_e32 v37, 0xffff0000, v126
	v_lshlrev_b32_e32 v38, 16, v127
	v_and_b32_e32 v39, 0xffff0000, v127
	v_sqrt_f32_e32 v47, v1
	v_max_f32_e32 v1, 0, v6
	v_sqrt_f32_e32 v6, v1
	v_max_f32_e32 v1, 0, v7
	v_sqrt_f32_e32 v7, v1
	s_nop 0
	v_pk_mul_f32 v[6:7], v[6:7], v[14:15]
	v_pk_mul_f32 v[14:15], v[46:47], v[20:21]
	s_nop 0
	v_pk_mul_f32 v[20:21], v[14:15], v[36:37]
	v_pk_mul_f32 v[14:15], v[42:43], v[16:17]
	v_pk_fma_f32 v[16:17], v[48:49], v[16:17], v[20:21]
	v_pk_mul_f32 v[36:37], v[6:7], v[38:39]
	s_nop 0
	v_pk_fma_f32 v[8:9], v[8:9], v[40:41], v[36:37]
	s_nop 0
	v_pk_mul_f32 v[6:7], v[44:45], v[40:41]
	s_nop 0
	s_nop 1
	s_nop 0
	s_waitcnt vmcnt(11)
	v_lshlrev_b32_e32 v18, 16, v128
	v_and_b32_e32 v19, 0xffff0000, v128
	v_pk_mul_f32 v[18:19], v[28:29], v[18:19]
	v_lshlrev_b32_e32 v40, 16, v129
	v_exp_f32_e32 v74, v18
	v_exp_f32_e32 v75, v19
	v_and_b32_e32 v41, 0xffff0000, v129
	v_pk_mul_f32 v[40:41], v[26:27], v[40:41]
	v_exp_f32_e32 v40, v40
	v_pk_fma_f32 v[76:77], v[74:75], v[74:75], 1.0 op_sel_hi:[1,1,0] neg_lo:[1,0,0] neg_hi:[1,0,0]
	v_exp_f32_e32 v41, v41
	v_max_f32_e32 v1, 0, v76
	v_pk_fma_f32 v[18:19], v[40:41], v[40:41], 1.0 op_sel_hi:[1,1,0] neg_lo:[1,0,0] neg_hi:[1,0,0]
	s_waitcnt vmcnt(10)
	v_lshlrev_b32_e32 v48, 16, v132
	v_and_b32_e32 v49, 0xffff0000, v132
	v_lshlrev_b32_e32 v62, 16, v133
	v_and_b32_e32 v63, 0xffff0000, v133
	v_pk_mul_f32 v[10:11], v[10:11], v[74:75]
	s_waitcnt vmcnt(9)
	v_lshlrev_b32_e32 v66, 16, v136
	v_sqrt_f32_e32 v76, v1
	v_max_f32_e32 v1, 0, v77
	v_and_b32_e32 v67, 0xffff0000, v136
	v_lshlrev_b32_e32 v70, 16, v137
	v_and_b32_e32 v71, 0xffff0000, v137
	v_sqrt_f32_e32 v77, v1
	v_max_f32_e32 v1, 0, v18
	v_pk_mul_f32 v[48:49], v[76:77], v[48:49]
	v_pk_mul_f32 v[48:49], v[48:49], v[66:67]
	v_sqrt_f32_e32 v18, v1
	v_max_f32_e32 v1, 0, v19
	v_sqrt_f32_e32 v19, v1
	s_nop 0
	v_pk_mul_f32 v[18:19], v[18:19], v[62:63]
	s_nop 0
	v_pk_mul_f32 v[62:63], v[18:19], v[70:71]
	v_pk_mul_f32 v[18:19], v[2:3], v[40:41]
	v_pk_fma_f32 v[2:3], v[12:13], v[74:75], v[48:49]
	v_pk_fma_f32 v[12:13], v[4:5], v[40:41], v[62:63]
	v_lshlrev_b32_e32 v4, 16, v130
	v_and_b32_e32 v5, 0xffff0000, v130
	v_pk_mul_f32 v[4:5], v[32:33], v[4:5]
	v_lshlrev_b32_e32 v40, 16, v131
	v_exp_f32_e32 v66, v4
	v_exp_f32_e32 v67, v5
	v_and_b32_e32 v41, 0xffff0000, v131
	v_pk_mul_f32 v[40:41], v[30:31], v[40:41]
	v_exp_f32_e32 v40, v40
	v_pk_fma_f32 v[70:71], v[66:67], v[66:67], 1.0 op_sel_hi:[1,1,0] neg_lo:[1,0,0] neg_hi:[1,0,0]
	v_exp_f32_e32 v41, v41
	v_max_f32_e32 v1, 0, v70
	v_pk_fma_f32 v[4:5], v[40:41], v[40:41], 1.0 op_sel_hi:[1,1,0] neg_lo:[1,0,0] neg_hi:[1,0,0]
	v_lshlrev_b32_e32 v48, 16, v134
	v_and_b32_e32 v49, 0xffff0000, v134
	v_lshlrev_b32_e32 v50, 16, v135
	v_and_b32_e32 v51, 0xffff0000, v135
	v_lshlrev_b32_e32 v62, 16, v138
	v_and_b32_e32 v63, 0xffff0000, v138
	v_sqrt_f32_e32 v70, v1
	v_max_f32_e32 v1, 0, v71
	v_lshlrev_b32_e32 v64, 16, v139
	v_and_b32_e32 v65, 0xffff0000, v139
	v_sqrt_f32_e32 v71, v1
	v_max_f32_e32 v1, 0, v4
	v_pk_mul_f32 v[48:49], v[70:71], v[48:49]
	v_pk_mul_f32 v[48:49], v[48:49], v[62:63]
	v_sqrt_f32_e32 v4, v1
	v_max_f32_e32 v1, 0, v5
	v_sqrt_f32_e32 v5, v1
	s_nop 0
	v_pk_mul_f32 v[4:5], v[4:5], v[50:51]
	s_nop 0
	v_pk_mul_f32 v[50:51], v[4:5], v[64:65]
	v_pk_mul_f32 v[4:5], v[14:15], v[66:67]
	v_pk_mul_f32 v[14:15], v[6:7], v[40:41]
	v_pk_fma_f32 v[6:7], v[16:17], v[66:67], v[48:49]
	v_pk_fma_f32 v[8:9], v[8:9], v[40:41], v[50:51]
	s_nop 0
	s_waitcnt vmcnt(8)
; __device__ __forceinline__ f32x4 unpack4(u32x2 u) { return (f32x4){__uint_as_float(u.x << 16), __uint_as_float(u.x & 0xffff0000u), __uint_as_float(u.y << 16), __uint_as_float(u.y & 0xffff0000u)}; }
; __device__ __forceinline__ float softplus_(float x) { return x > 20.f ? x : log1pf(expf(x)); }
; template <int ph>
; __device__ __forceinline__ void run_phase(const Args& args, LAS unsigned char* lds, const int G, const int bx, const bool fin = true) {
;     ...
;             auto lru_ab = [](f32x4 gr, f32x4 gi, f32x4 xc, f32x4 sp, f32x4& a, f32x4& bb) {
;                 const f32x4 la = gr * sp; a = (f32x4){__expf(la[0]), __expf(la[1]), __expf(la[2]), __expf(la[3])};
;                 const f32x4 om = (f32x4){1.f, 1.f, 1.f, 1.f} - a * a;
;                 bb = (f32x4){sqrtf(fmaxf(om[0], 0.f)), sqrtf(fmaxf(om[1], 0.f)), sqrtf(fmaxf(om[2], 0.f)), sqrtf(fmaxf(om[3], 0.f))} * gi * xc; };
;             for (int unit = bx; unit < 128; unit += G) {
;                 const int b = unit >> 4, l8 = tid & 7, ch = (unit & 15) * 64 + 8 * l8, seg = tid >> 3, t0 = seg * 32;
;                 const f32x4 lam0 = *(const f32x4*)(lru_lambda + ch), lam1 = *(const f32x4*)(lru_lambda + ch + 4);
;                 const f32x4 sp0 = (f32x4){softplus_(-lam0[0]), softplus_(-lam0[1]), softplus_(-lam0[2]), softplus_(-lam0[3])} * -8.0f,
;                             sp1 = (f32x4){softplus_(-lam1[0]), softplus_(-lam1[1]), softplus_(-lam1[2]), softplus_(-lam1[3])} * -8.0f;
;                 const size_t base = ((size_t)b * T + t0) * D + ch;
;                 f32x4 A0 = (f32x4){1.f, 1.f, 1.f, 1.f}, A1 = A0, B0 = (f32x4){0.f, 0.f, 0.f, 0.f}, B1 = B0;
; #pragma unroll 8
;                 for (int t = 0; t < 32; ++t) { const size_t o = base + (size_t)t * D;
;                     const u32x4 gr = *(const u32x4*)(GR + o), gi = *(const u32x4*)(GI + o), xc = *(const u32x4*)(XC + o);
;                     f32x4 a, bb;
;                     lru_ab(unpack4((u32x2){gr.x, gr.y}), unpack4((u32x2){gi.x, gi.y}), unpack4((u32x2){xc.x, xc.y}), sp0, a, bb); A0 = A0 * a; B0 = a * B0 + bb;
;                     lru_ab(unpack4((u32x2){gr.z, gr.w}), unpack4((u32x2){gi.z, gi.w}), unpack4((u32x2){xc.z, xc.w}), sp1, a, bb); A1 = A1 * a; B1 = a * B1 + bb; }
	v_lshlrev_b32_e32 v16, 16, v140
	v_and_b32_e32 v17, 0xffff0000, v140
	v_pk_mul_f32 v[16:17], v[28:29], v[16:17]
	v_lshlrev_b32_e32 v20, 16, v141
	v_exp_f32_e32 v66, v16
	v_exp_f32_e32 v67, v17
	v_and_b32_e32 v21, 0xffff0000, v141
	v_pk_mul_f32 v[20:21], v[26:27], v[20:21]
	v_exp_f32_e32 v20, v20
	v_pk_fma_f32 v[70:71], v[66:67], v[66:67], 1.0 op_sel_hi:[1,1,0] neg_lo:[1,0,0] neg_hi:[1,0,0]
	v_exp_f32_e32 v21, v21
	v_max_f32_e32 v1, 0, v70
	v_pk_fma_f32 v[16:17], v[20:21], v[20:21], 1.0 op_sel_hi:[1,1,0] neg_lo:[1,0,0] neg_hi:[1,0,0]
	s_waitcnt vmcnt(7)
	v_lshlrev_b32_e32 v40, 16, v144
	v_and_b32_e32 v41, 0xffff0000, v144
	v_lshlrev_b32_e32 v48, 16, v145
	v_and_b32_e32 v49, 0xffff0000, v145
	s_waitcnt vmcnt(6)
	v_lshlrev_b32_e32 v62, 16, v148
	v_and_b32_e32 v63, 0xffff0000, v148
	v_sqrt_f32_e32 v70, v1
	v_max_f32_e32 v1, 0, v71
	v_lshlrev_b32_e32 v36, 16, v149
	v_and_b32_e32 v37, 0xffff0000, v149
	v_sqrt_f32_e32 v71, v1
	v_max_f32_e32 v1, 0, v16
	v_pk_mul_f32 v[40:41], v[70:71], v[40:41]
	v_pk_mul_f32 v[40:41], v[40:41], v[62:63]
	v_sqrt_f32_e32 v16, v1
	v_max_f32_e32 v1, 0, v17
	v_sqrt_f32_e32 v17, v1
	s_nop 0
	v_pk_mul_f32 v[16:17], v[16:17], v[48:49]
	v_lshlrev_b32_e32 v48, 16, v150
	v_pk_mul_f32 v[36:37], v[16:17], v[36:37]
	v_pk_mul_f32 v[16:17], v[18:19], v[20:21]
	v_pk_mul_f32 v[18:19], v[10:11], v[66:67]
	v_pk_fma_f32 v[10:11], v[12:13], v[20:21], v[36:37]
	v_pk_fma_f32 v[20:21], v[2:3], v[66:67], v[40:41]
	v_lshlrev_b32_e32 v2, 16, v142
	v_and_b32_e32 v3, 0xffff0000, v142
	v_pk_mul_f32 v[2:3], v[32:33], v[2:3]
	v_lshlrev_b32_e32 v12, 16, v143
	v_exp_f32_e32 v2, v2
	v_exp_f32_e32 v3, v3
	v_and_b32_e32 v13, 0xffff0000, v143
	v_pk_mul_f32 v[12:13], v[30:31], v[12:13]
	v_exp_f32_e32 v50, v12
	v_pk_fma_f32 v[62:63], v[2:3], v[2:3], 1.0 op_sel_hi:[1,1,0] neg_lo:[1,0,0] neg_hi:[1,0,0]
	v_exp_f32_e32 v51, v13
	v_max_f32_e32 v1, 0, v62
	v_pk_fma_f32 v[12:13], v[50:51], v[50:51], 1.0 op_sel_hi:[1,1,0] neg_lo:[1,0,0] neg_hi:[1,0,0]
	v_lshlrev_b32_e32 v36, 16, v146
	v_and_b32_e32 v37, 0xffff0000, v146
	v_lshlrev_b32_e32 v40, 16, v147
	v_and_b32_e32 v41, 0xffff0000, v147
	v_and_b32_e32 v49, 0xffff0000, v150
	v_lshlrev_b32_e32 v38, 16, v151
	v_sqrt_f32_e32 v62, v1
	v_max_f32_e32 v1, 0, v63
	v_and_b32_e32 v39, 0xffff0000, v151
	v_sqrt_f32_e32 v63, v1
	v_max_f32_e32 v1, 0, v12
	v_pk_mul_f32 v[36:37], v[62:63], v[36:37]
	v_pk_mul_f32 v[36:37], v[36:37], v[48:49]
	v_pk_fma_f32 v[36:37], v[6:7], v[2:3], v[36:37]
	v_sqrt_f32_e32 v12, v1
	v_max_f32_e32 v1, 0, v13
	v_sqrt_f32_e32 v13, v1
	s_nop 0
	v_pk_mul_f32 v[12:13], v[12:13], v[40:41]
	s_nop 0
	v_pk_mul_f32 v[38:39], v[12:13], v[38:39]
	v_pk_mul_f32 v[12:13], v[14:15], v[50:51]
	v_pk_mul_f32 v[14:15], v[4:5], v[2:3]
	v_pk_fma_f32 v[8:9], v[8:9], v[50:51], v[38:39]
	s_waitcnt vmcnt(5)
	v_lshlrev_b32_e32 v6, 16, v152
	v_and_b32_e32 v7, 0xffff0000, v152
	v_pk_mul_f32 v[6:7], v[28:29], v[6:7]
	v_lshlrev_b32_e32 v2, 16, v153
	v_exp_f32_e32 v66, v6
	v_exp_f32_e32 v67, v7
	v_and_b32_e32 v3, 0xffff0000, v153
	v_pk_mul_f32 v[2:3], v[26:27], v[2:3]
	v_exp_f32_e32 v70, v2
	v_pk_fma_f32 v[6:7], v[66:67], v[66:67], 1.0 op_sel_hi:[1,1,0] neg_lo:[1,0,0] neg_hi:[1,0,0]
	v_exp_f32_e32 v71, v3
	v_max_f32_e32 v1, 0, v6
	v_pk_fma_f32 v[2:3], v[70:71], v[70:71], 1.0 op_sel_hi:[1,1,0] neg_lo:[1,0,0] neg_hi:[1,0,0]
	s_waitcnt vmcnt(4)
	v_lshlrev_b32_e32 v48, 16, v156
	v_and_b32_e32 v49, 0xffff0000, v156
	v_lshlrev_b32_e32 v38, 16, v157
	v_and_b32_e32 v39, 0xffff0000, v157
	s_waitcnt vmcnt(3)
	v_lshlrev_b32_e32 v50, 16, v160
	v_and_b32_e32 v51, 0xffff0000, v160
	v_sqrt_f32_e32 v6, v1
	v_max_f32_e32 v1, 0, v7
	v_lshlrev_b32_e32 v62, 16, v161
	v_and_b32_e32 v63, 0xffff0000, v161
	v_sqrt_f32_e32 v7, v1
	v_max_f32_e32 v1, 0, v2
	v_pk_mul_f32 v[6:7], v[6:7], v[48:49]
	v_pk_mul_f32 v[48:49], v[6:7], v[50:51]
	v_pk_mul_f32 v[6:7], v[16:17], v[70:71]
	v_lshlrev_b32_e32 v16, 16, v158
	v_and_b32_e32 v17, 0xffff0000, v158
	v_pk_fma_f32 v[48:49], v[20:21], v[66:67], v[48:49]
	v_lshlrev_b32_e32 v20, 16, v162
	v_and_b32_e32 v21, 0xffff0000, v162
	s_nop 0
	v_sqrt_f32_e32 v2, v1
	v_max_f32_e32 v1, 0, v3
	v_sqrt_f32_e32 v3, v1
	s_nop 0
	v_pk_mul_f32 v[2:3], v[2:3], v[38:39]
	s_nop 0
	v_pk_mul_f32 v[38:39], v[2:3], v[62:63]
	v_pk_mul_f32 v[2:3], v[18:19], v[66:67]
	v_pk_fma_f32 v[50:51], v[10:11], v[70:71], v[38:39]
	v_lshlrev_b32_e32 v10, 16, v154
	v_and_b32_e32 v11, 0xffff0000, v154
	v_pk_mul_f32 v[10:11], v[32:33], v[10:11]
	v_lshlrev_b32_e32 v4, 16, v155
	v_exp_f32_e32 v10, v10
	v_exp_f32_e32 v11, v11
	v_and_b32_e32 v5, 0xffff0000, v155
	v_pk_mul_f32 v[4:5], v[30:31], v[4:5]
	v_exp_f32_e32 v4, v4
	v_pk_fma_f32 v[62:63], v[10:11], v[10:11], 1.0 op_sel_hi:[1,1,0] neg_lo:[1,0,0] neg_hi:[1,0,0]
	v_exp_f32_e32 v5, v5
	v_max_f32_e32 v1, 0, v62
	v_lshlrev_b32_e32 v18, 16, v159
	v_and_b32_e32 v19, 0xffff0000, v159
	v_pk_fma_f32 v[40:41], v[4:5], v[4:5], 1.0 op_sel_hi:[1,1,0] neg_lo:[1,0,0] neg_hi:[1,0,0]
	v_lshlrev_b32_e32 v38, 16, v163
	v_and_b32_e32 v39, 0xffff0000, v163
	v_sqrt_f32_e32 v62, v1
	v_max_f32_e32 v1, 0, v63
	v_sqrt_f32_e32 v63, v1
	v_max_f32_e32 v1, 0, v40
	v_pk_mul_f32 v[16:17], v[62:63], v[16:17]
	v_pk_mul_f32 v[16:17], v[16:17], v[20:21]
	v_pk_mul_f32 v[20:21], v[14:15], v[10:11]
	v_pk_fma_f32 v[36:37], v[36:37], v[10:11], v[16:17]
	v_sqrt_f32_e32 v40, v1
	v_max_f32_e32 v1, 0, v41
	v_sqrt_f32_e32 v41, v1
	s_nop 0
	v_pk_mul_f32 v[18:19], v[40:41], v[18:19]
	s_nop 0
	v_pk_mul_f32 v[18:19], v[18:19], v[38:39]
	v_pk_mul_f32 v[38:39], v[12:13], v[4:5]
	v_pk_fma_f32 v[40:41], v[8:9], v[4:5], v[18:19]
	s_waitcnt vmcnt(2)
; __device__ __forceinline__ f32x4 unpack4(u32x2 u) { return (f32x4){__uint_as_float(u.x << 16), __uint_as_float(u.x & 0xffff0000u), __uint_as_float(u.y << 16), __uint_as_float(u.y & 0xffff0000u)}; }
; template <int ph>
; __device__ __forceinline__ void run_phase(const Args& args, LAS unsigned char* lds, const int G, const int bx, const bool fin = true) {
;     ...
; #pragma unroll 8
;                 for (int t = 0; t < 32; ++t) { const size_t o = base + (size_t)t * D;
;                     const u32x4 gr = *(const u32x4*)(GR + o), gi = *(const u32x4*)(GI + o), xc = *(const u32x4*)(XC + o);
;                     f32x4 a, bb;
;                     lru_ab(unpack4((u32x2){gr.x, gr.y}), unpack4((u32x2){gi.x, gi.y}), unpack4((u32x2){xc.x, xc.y}), sp0, a, bb); A0 = A0 * a; B0 = a * B0 + bb;
;                     lru_ab(unpack4((u32x2){gr.z, gr.w}), unpack4((u32x2){gi.z, gi.w}), unpack4((u32x2){xc.z, xc.w}), sp1, a, bb); A1 = A1 * a; B1 = a * B1 + bb; }
;                 sA[(seg * 8 + l8) * 2] = A0; sA[(seg * 8 + l8) * 2 + 1] = A1; sB[(seg * 8 + l8) * 2] = B0; sB[(seg * 8 + l8) * 2 + 1] = B1;
;                 __syncthreads();
;                 f32x4 h0 = (f32x4){0.f, 0.f, 0.f, 0.f}, h1 = h0;
;                 for (int s2 = 0; s2 < seg; ++s2) { h0 = sA[(s2 * 8 + l8) * 2] * h0 + sB[(s2 * 8 + l8) * 2]; h1 = sA[(s2 * 8 + l8) * 2 + 1] * h1 + sB[(s2 * 8 + l8) * 2 + 1]; }
	v_lshlrev_b32_e32 v4, 16, v164
	v_and_b32_e32 v5, 0xffff0000, v164
	v_pk_mul_f32 v[4:5], v[28:29], v[4:5]
	v_lshlrev_b32_e32 v16, 16, v165
	v_exp_f32_e32 v46, v4
	v_exp_f32_e32 v47, v5
	v_and_b32_e32 v17, 0xffff0000, v165
	v_pk_mul_f32 v[16:17], v[26:27], v[16:17]
	v_exp_f32_e32 v4, v16
	v_pk_fma_f32 v[62:63], v[46:47], v[46:47], 1.0 op_sel_hi:[1,1,0] neg_lo:[1,0,0] neg_hi:[1,0,0]
	v_exp_f32_e32 v5, v17
	v_max_f32_e32 v1, 0, v62
	v_pk_fma_f32 v[16:17], v[4:5], v[4:5], 1.0 op_sel_hi:[1,1,0] neg_lo:[1,0,0] neg_hi:[1,0,0]
	s_waitcnt vmcnt(1)
	v_lshlrev_b32_e32 v42, 16, v168
	v_and_b32_e32 v43, 0xffff0000, v168
	v_lshlrev_b32_e32 v12, 16, v169
	v_and_b32_e32 v13, 0xffff0000, v169
	s_waitcnt vmcnt(0)
	v_lshlrev_b32_e32 v44, 16, v172
	v_and_b32_e32 v45, 0xffff0000, v172
	v_sqrt_f32_e32 v62, v1
	v_max_f32_e32 v1, 0, v63
	v_lshlrev_b32_e32 v8, 16, v173
	v_and_b32_e32 v9, 0xffff0000, v173
	v_sqrt_f32_e32 v63, v1
	v_max_f32_e32 v1, 0, v16
	v_sqrt_f32_e32 v16, v1
	v_max_f32_e32 v1, 0, v17
	v_sqrt_f32_e32 v17, v1
	s_nop 0
	v_pk_mul_f32 v[12:13], v[16:17], v[12:13]
	v_pk_mul_f32 v[16:17], v[62:63], v[42:43]
	v_pk_mul_f32 v[12:13], v[12:13], v[8:9]
	v_pk_mul_f32 v[16:17], v[16:17], v[44:45]
	v_pk_mul_f32 v[8:9], v[6:7], v[4:5]
	v_pk_mul_f32 v[6:7], v[2:3], v[46:47]
	v_pk_fma_f32 v[2:3], v[48:49], v[46:47], v[16:17]
	v_lshlrev_b32_e32 v16, 16, v166
	v_and_b32_e32 v17, 0xffff0000, v166
	v_pk_fma_f32 v[4:5], v[50:51], v[4:5], v[12:13]
	v_lshlrev_b32_e32 v12, 16, v170
	v_and_b32_e32 v13, 0xffff0000, v170
	v_lshlrev_b32_e32 v42, 16, v171
	v_and_b32_e32 v43, 0xffff0000, v171
	v_pk_mul_f32 v[14:15], v[32:33], v[16:17]
	v_lshlrev_b32_e32 v44, 16, v167
	v_exp_f32_e32 v14, v14
	v_exp_f32_e32 v15, v15
	v_and_b32_e32 v45, 0xffff0000, v167
	v_pk_mul_f32 v[44:45], v[30:31], v[44:45]
	v_exp_f32_e32 v16, v44
	v_pk_fma_f32 v[46:47], v[14:15], v[14:15], 1.0 op_sel_hi:[1,1,0] neg_lo:[1,0,0] neg_hi:[1,0,0]
	v_exp_f32_e32 v17, v45
	v_max_f32_e32 v1, 0, v46
	v_pk_fma_f32 v[44:45], v[16:17], v[16:17], 1.0 op_sel_hi:[1,1,0] neg_lo:[1,0,0] neg_hi:[1,0,0]
	v_lshlrev_b32_e32 v18, 16, v174
	v_and_b32_e32 v19, 0xffff0000, v174
	v_lshlrev_b32_e32 v10, 16, v175
	v_and_b32_e32 v11, 0xffff0000, v175
	v_sqrt_f32_e32 v46, v1
	v_max_f32_e32 v1, 0, v47
	v_sqrt_f32_e32 v47, v1
	v_max_f32_e32 v1, 0, v44
	v_pk_mul_f32 v[12:13], v[46:47], v[12:13]
	v_pk_mul_f32 v[18:19], v[12:13], v[18:19]
	v_pk_mul_f32 v[12:13], v[38:39], v[16:17]
	v_sqrt_f32_e32 v44, v1
	v_max_f32_e32 v1, 0, v45
	v_sqrt_f32_e32 v45, v1
	s_nop 0
	v_pk_mul_f32 v[42:43], v[44:45], v[42:43]
	s_nop 0
	v_pk_mul_f32 v[42:43], v[42:43], v[10:11]
	v_pk_mul_f32 v[10:11], v[20:21], v[14:15]
	v_pk_fma_f32 v[16:17], v[40:41], v[16:17], v[42:43]
	v_pk_fma_f32 v[14:15], v[36:37], v[14:15], v[18:19]
	s_cbranch_scc0 .LBB0_1061
	ds_write_b128 v53, v[6:9]
	ds_write_b128 v53, v[10:13] offset:16
	ds_write_b128 v53, v[2:5] offset:16384
	ds_write_b128 v53, v[14:17] offset:16400
	v_mov_b32_e32 v9, 0
	v_mov_b32_e32 v8, 0
	v_mov_b32_e32 v7, 0
	v_mov_b32_e32 v6, 0
	v_mov_b32_e32 v5, 0
	v_mov_b32_e32 v4, 0
	v_mov_b32_e32 v3, 0
	v_mov_b32_e32 v2, 0
	s_waitcnt lgkmcnt(0)
	s_barrier
	s_and_saveexec_b64 s[0:1], s[2:3]
	s_cbranch_execz .LBB0_1072
	v_mov_b32_e32 v2, v0
	v_mov_b32_e32 v3, v0
	v_mov_b32_e32 v1, v0
	v_mov_b64_e32 v[8:9], v[2:3]
	v_mov_b64_e32 v[6:7], v[0:1]
	v_mov_b64_e32 v[4:5], v[2:3]
	v_mov_b32_e32 v10, 0
	v_mov_b64_e32 v[2:3], v[0:1]
	s_and_saveexec_b64 s[24:25], s[6:7]
	s_cbranch_execz .LBB0_1067
	v_mov_b32_e32 v2, 0
	s_mov_b32 s10, 0
	s_mov_b64 s[26:27], 0
	v_mov_b32_e32 v1, v56
	v_mov_b32_e32 v3, v2
	v_mov_b32_e32 v4, v2
	v_mov_b32_e32 v5, v2
	v_mov_b32_e32 v6, v2
	v_mov_b32_e32 v7, v2
	v_mov_b32_e32 v8, v2
	v_mov_b32_e32 v9, v2

; __device__ __forceinline__ f32x4 unpack4(u32x2 u) { return (f32x4){__uint_as_float(u.x << 16), __uint_as_float(u.x & 0xffff0000u), __uint_as_float(u.y << 16), __uint_as_float(u.y & 0xffff0000u)}; }
; __device__ __forceinline__ u32x2 pack4(f32x4 v) { u32x2 r; r.x = cvt_pk_bf16(v.x, v.y); r.y = cvt_pk_bf16(v.z, v.w); return r; }
; template <int ph>
; __device__ __forceinline__ void run_phase(const Args& args, LAS unsigned char* lds, const int G, const int bx, const bool fin = true) {
;     ...
;             auto lru_ab = [](f32x4 gr, f32x4 gi, f32x4 xc, f32x4 sp, f32x4& a, f32x4& bb) {
;                 const f32x4 la = gr * sp; a = (f32x4){__expf(la[0]), __expf(la[1]), __expf(la[2]), __expf(la[3])};
;                 const f32x4 om = (f32x4){1.f, 1.f, 1.f, 1.f} - a * a;
;                 bb = (f32x4){sqrtf(fmaxf(om[0], 0.f)), sqrtf(fmaxf(om[1], 0.f)), sqrtf(fmaxf(om[2], 0.f)), sqrtf(fmaxf(om[3], 0.f))} * gi * xc; };
;     ...
; #pragma unroll 8
;                 for (int t = 0; t < 32; ++t) { const size_t o = base + (size_t)t * D;
;                     const u32x4 gr = *(const u32x4*)(GR + o), gi = *(const u32x4*)(GI + o), xc = *(const u32x4*)(XC + o), gg = *(const u32x4*)(GG + o);
;                     f32x4 a, bb;
;                     lru_ab(unpack4((u32x2){gr.x, gr.y}), unpack4((u32x2){gi.x, gi.y}), unpack4((u32x2){xc.x, xc.y}), sp0, a, bb); h0 = a * h0 + bb;
;                     lru_ab(unpack4((u32x2){gr.z, gr.w}), unpack4((u32x2){gi.z, gi.w}), unpack4((u32x2){xc.z, xc.w}), sp1, a, bb); h1 = a * h1 + bb;
;                     const u32x2 w0 = pack4(h0 * unpack4((u32x2){gg.x, gg.y})), w1 = pack4(h1 * unpack4((u32x2){gg.z, gg.w}));
;                     *(u32x4*)(LO + o) = (u32x4){w0.x, w0.y, w1.x, w1.y}; }
.LBB0_1073:
	s_nop 0
	v_lshl_add_u64 v[10:11], v[34:35], 0, s[24:25]
	v_add_co_u32_e32 v200, vcc, 0x10700000, v10
	s_nop 1
	v_addc_co_u32_e32 v201, vcc, 0, v11, vcc
	v_add_co_u32_e32 v212, vcc, 0x16a00000, v10
	s_nop 1
	v_addc_co_u32_e32 v213, vcc, 0, v11, vcc
	v_add_co_u32_e32 v214, vcc, 0x7d80000, v10
	s_nop 1
	v_addc_co_u32_e32 v215, vcc, 0, v11, vcc
	v_add_co_u32_e32 v216, vcc, 0x12800000, v10
	s_nop 1
	v_addc_co_u32_e32 v217, vcc, 0, v11, vcc
	v_add_co_u32_e32 v218, vcc, s52, v10
	s_nop 1
	v_addc_co_u32_e32 v219, vcc, 0, v11, vcc
	v_add_co_u32_e32 v220, vcc, s55, v10
	s_nop 1
	v_addc_co_u32_e32 v221, vcc, 0, v11, vcc
	v_add_co_u32_e32 v222, vcc, s53, v10
	s_nop 1
	v_addc_co_u32_e32 v223, vcc, 0, v11, vcc
	v_add_co_u32_e32 v224, vcc, s56, v10
	s_nop 1
	v_addc_co_u32_e32 v225, vcc, 0, v11, vcc
	v_add_co_u32_e32 v226, vcc, s54, v10
	s_nop 1
	v_addc_co_u32_e32 v227, vcc, 0, v11, vcc
	v_add_co_u32_e32 v230, vcc, s57, v10
	s_nop 1
	v_addc_co_u32_e32 v231, vcc, 0, v11, vcc
	v_add_co_u32_e32 v232, vcc, s75, v10
	s_nop 1
	v_addc_co_u32_e32 v233, vcc, 0, v11, vcc
	v_add_co_u32_e32 v234, vcc, s76, v10
	s_nop 1
	v_addc_co_u32_e32 v235, vcc, 0, v11, vcc
	v_add_co_u32_e32 v236, vcc, s62, v10
	s_nop 1
	v_addc_co_u32_e32 v237, vcc, 0, v11, vcc
	v_add_co_u32_e32 v238, vcc, s63, v10
	s_nop 1
	v_addc_co_u32_e32 v239, vcc, 0, v11, vcc
	v_add_co_u32_e32 v240, vcc, s74, v10
	s_nop 1
	v_addc_co_u32_e32 v241, vcc, 0, v11, vcc
	v_add_co_u32_e32 v242, vcc, s77, v10
	s_nop 1
	v_addc_co_u32_e32 v243, vcc, 0, v11, vcc
	global_load_dwordx4 v[80:83], v[200:201], off
	global_load_dwordx4 v[84:87], v[212:213], off
	global_load_dwordx4 v[88:91], v[214:215], off
	global_load_dwordx4 v[92:95], v[216:217], off
	global_load_dwordx4 v[96:99], v[200:201], off offset:2048
	global_load_dwordx4 v[100:103], v[212:213], off offset:2048
	global_load_dwordx4 v[104:107], v[214:215], off offset:2048
	global_load_dwordx4 v[108:111], v[216:217], off offset:2048
	global_load_dwordx4 v[112:115], v[220:221], off offset:-4096
	global_load_dwordx4 v[116:119], v[224:225], off offset:-4096
	global_load_dwordx4 v[120:123], v[230:231], off offset:-4096
	global_load_dwordx4 v[124:127], v[234:235], off offset:-4096
	global_load_dwordx4 v[128:131], v[218:219], off offset:2048
	global_load_dwordx4 v[132:135], v[222:223], off offset:2048
	global_load_dwordx4 v[136:139], v[226:227], off offset:2048
	global_load_dwordx4 v[140:143], v[232:233], off offset:2048
	global_load_dwordx4 v[144:147], v[220:221], off
	global_load_dwordx4 v[148:151], v[224:225], off
	global_load_dwordx4 v[152:155], v[230:231], off
	global_load_dwordx4 v[156:159], v[234:235], off
	global_load_dwordx4 v[160:163], v[220:221], off offset:2048
	global_load_dwordx4 v[164:167], v[224:225], off offset:2048
	global_load_dwordx4 v[168:171], v[230:231], off offset:2048
	global_load_dwordx4 v[172:175], v[234:235], off offset:2048
	global_load_dwordx4 v[176:179], v[236:237], off
	global_load_dwordx4 v[180:183], v[238:239], off
	global_load_dwordx4 v[184:187], v[240:241], off
	global_load_dwordx4 v[188:191], v[242:243], off
	global_load_dwordx4 v[192:195], v[236:237], off offset:2048
	global_load_dwordx4 v[196:199], v[238:239], off offset:2048
	global_load_dwordx4 v[204:207], v[240:241], off offset:2048
	global_load_dwordx4 v[208:211], v[242:243], off offset:2048
	s_add_u32 s24, s24, 0x4000
	s_nop 0
	s_addc_u32 s25, s25, 0
	s_nop 0
	s_nop 0
	s_cmp_eq_u32 s24, 0x10000
	s_nop 0
	s_waitcnt vmcnt(31)
	v_lshlrev_b32_e32 v50, 16, v80
	v_and_b32_e32 v51, 0xffff0000, v80
	v_pk_mul_f32 v[50:51], v[28:29], v[50:51]
	v_lshlrev_b32_e32 v14, 16, v81
	v_exp_f32_e32 v50, v50
	v_exp_f32_e32 v51, v51
	v_and_b32_e32 v15, 0xffff0000, v81
	v_pk_mul_f32 v[14:15], v[26:27], v[14:15]
	v_exp_f32_e32 v14, v14
	v_pk_fma_f32 v[70:71], v[50:51], v[50:51], 1.0 op_sel_hi:[1,1,0] neg_lo:[1,0,0] neg_hi:[1,0,0]
	v_exp_f32_e32 v15, v15
	v_max_f32_e32 v1, 0, v70
	v_pk_fma_f32 v[66:67], v[14:15], v[14:15], 1.0 op_sel_hi:[1,1,0] neg_lo:[1,0,0] neg_hi:[1,0,0]
	s_waitcnt vmcnt(30)
	v_lshlrev_b32_e32 v62, 16, v84
	v_and_b32_e32 v63, 0xffff0000, v84
	v_lshlrev_b32_e32 v18, 16, v85
	v_and_b32_e32 v19, 0xffff0000, v85
	s_waitcnt vmcnt(29)
	v_lshlrev_b32_e32 v64, 16, v88
	v_and_b32_e32 v65, 0xffff0000, v88
	v_sqrt_f32_e32 v70, v1
	v_max_f32_e32 v1, 0, v71
	v_lshlrev_b32_e32 v36, 16, v89
	v_and_b32_e32 v37, 0xffff0000, v89
	v_sqrt_f32_e32 v71, v1
	v_max_f32_e32 v1, 0, v66
	v_pk_mul_f32 v[62:63], v[70:71], v[62:63]
	v_sqrt_f32_e32 v66, v1
	v_max_f32_e32 v1, 0, v67
	v_sqrt_f32_e32 v67, v1
	s_nop 0
	v_pk_mul_f32 v[18:19], v[66:67], v[18:19]
	s_nop 0
	v_pk_mul_f32 v[18:19], v[18:19], v[36:37]
	v_pk_mul_f32 v[36:37], v[62:63], v[64:65]
	v_pk_fma_f32 v[62:63], v[4:5], v[14:15], v[18:19]
	v_pk_fma_f32 v[50:51], v[2:3], v[50:51], v[36:37]
	v_lshlrev_b32_e32 v2, 16, v82
	v_and_b32_e32 v3, 0xffff0000, v82
	v_pk_mul_f32 v[2:3], v[32:33], v[2:3]
	v_lshlrev_b32_e32 v4, 16, v83
	v_exp_f32_e32 v2, v2
	v_exp_f32_e32 v3, v3
	v_and_b32_e32 v5, 0xffff0000, v83
	v_pk_mul_f32 v[4:5], v[30:31], v[4:5]
	v_lshlrev_b32_e32 v14, 16, v86
	v_and_b32_e32 v15, 0xffff0000, v86
	v_lshlrev_b32_e32 v16, 16, v87
	v_and_b32_e32 v17, 0xffff0000, v87
	v_lshlrev_b32_e32 v18, 16, v90
	v_and_b32_e32 v19, 0xffff0000, v90
	v_lshlrev_b32_e32 v20, 16, v91
	v_and_b32_e32 v21, 0xffff0000, v91
	v_exp_f32_e32 v4, v4
	v_pk_fma_f32 v[38:39], v[2:3], v[2:3], 1.0 op_sel_hi:[1,1,0] neg_lo:[1,0,0] neg_hi:[1,0,0]
	v_exp_f32_e32 v5, v5
	v_max_f32_e32 v1, 0, v38
	v_pk_fma_f32 v[36:37], v[4:5], v[4:5], 1.0 op_sel_hi:[1,1,0] neg_lo:[1,0,0] neg_hi:[1,0,0]
	v_sqrt_f32_e32 v38, v1
	v_max_f32_e32 v1, 0, v39
	v_sqrt_f32_e32 v39, v1
	v_max_f32_e32 v1, 0, v36
	v_pk_mul_f32 v[14:15], v[38:39], v[14:15]
	v_pk_mul_f32 v[14:15], v[14:15], v[18:19]
	v_pk_fma_f32 v[64:65], v[6:7], v[2:3], v[14:15]
	s_waitcnt vmcnt(28)
; __device__ __forceinline__ f32x4 unpack4(u32x2 u) { return (f32x4){__uint_as_float(u.x << 16), __uint_as_float(u.x & 0xffff0000u), __uint_as_float(u.y << 16), __uint_as_float(u.y & 0xffff0000u)}; }
; __device__ __forceinline__ u32x2 pack4(f32x4 v) { u32x2 r; r.x = cvt_pk_bf16(v.x, v.y); r.y = cvt_pk_bf16(v.z, v.w); return r; }
; template <int ph>
; __device__ __forceinline__ void run_phase(const Args& args, LAS unsigned char* lds, const int G, const int bx, const bool fin = true) {
;     ...
;             auto lru_ab = [](f32x4 gr, f32x4 gi, f32x4 xc, f32x4 sp, f32x4& a, f32x4& bb) {
;                 const f32x4 la = gr * sp; a = (f32x4){__expf(la[0]), __expf(la[1]), __expf(la[2]), __expf(la[3])};
;                 const f32x4 om = (f32x4){1.f, 1.f, 1.f, 1.f} - a * a;
;                 bb = (f32x4){sqrtf(fmaxf(om[0], 0.f)), sqrtf(fmaxf(om[1], 0.f)), sqrtf(fmaxf(om[2], 0.f)), sqrtf(fmaxf(om[3], 0.f))} * gi * xc; };
;     ...
; #pragma unroll 8
;                 for (int t = 0; t < 32; ++t) { const size_t o = base + (size_t)t * D;
;                     const u32x4 gr = *(const u32x4*)(GR + o), gi = *(const u32x4*)(GI + o), xc = *(const u32x4*)(XC + o), gg = *(const u32x4*)(GG + o);
;                     f32x4 a, bb;
;                     lru_ab(unpack4((u32x2){gr.x, gr.y}), unpack4((u32x2){gi.x, gi.y}), unpack4((u32x2){xc.x, xc.y}), sp0, a, bb); h0 = a * h0 + bb;
;                     lru_ab(unpack4((u32x2){gr.z, gr.w}), unpack4((u32x2){gi.z, gi.w}), unpack4((u32x2){xc.z, xc.w}), sp1, a, bb); h1 = a * h1 + bb;
;                     const u32x2 w0 = pack4(h0 * unpack4((u32x2){gg.x, gg.y})), w1 = pack4(h1 * unpack4((u32x2){gg.z, gg.w}));
;                     *(u32x4*)(LO + o) = (u32x4){w0.x, w0.y, w1.x, w1.y}; }
	v_lshlrev_b32_e32 v2, 16, v92
	v_and_b32_e32 v3, 0xffff0000, v92
	v_pk_mul_f32 v[2:3], v[50:51], v[2:3]
	v_lshlrev_b32_e32 v6, 16, v95
	v_sqrt_f32_e32 v36, v1
	v_max_f32_e32 v1, 0, v37
	v_cvt_pk_bf16_f32 v2, v2, v3
	v_and_b32_e32 v7, 0xffff0000, v95
	v_sqrt_f32_e32 v37, v1
	s_nop 0
	v_pk_mul_f32 v[16:17], v[36:37], v[16:17]
	s_nop 0
	v_pk_mul_f32 v[16:17], v[16:17], v[20:21]
	s_nop 0
	v_pk_fma_f32 v[8:9], v[8:9], v[4:5], v[16:17]
	v_lshlrev_b32_e32 v4, 16, v93
	v_and_b32_e32 v5, 0xffff0000, v93
	v_pk_mul_f32 v[4:5], v[62:63], v[4:5]
	v_pk_mul_f32 v[6:7], v[8:9], v[6:7]
	v_cvt_pk_bf16_f32 v3, v4, v5
	v_lshlrev_b32_e32 v4, 16, v94
	v_and_b32_e32 v5, 0xffff0000, v94
	v_pk_mul_f32 v[4:5], v[64:65], v[4:5]
	s_nop 0
	v_cvt_pk_bf16_f32 v4, v4, v5
	v_cvt_pk_bf16_f32 v5, v6, v7
	global_store_dwordx4 v[212:213], v[2:5], off
	s_nop 0
	s_waitcnt vmcnt(28)
	v_lshlrev_b32_e32 v2, 16, v96
	v_and_b32_e32 v3, 0xffff0000, v96
	v_pk_mul_f32 v[2:3], v[28:29], v[2:3]
	v_lshlrev_b32_e32 v4, 16, v97
	v_exp_f32_e32 v2, v2
	v_exp_f32_e32 v3, v3
	v_and_b32_e32 v5, 0xffff0000, v97
	v_pk_mul_f32 v[4:5], v[26:27], v[4:5]
	v_exp_f32_e32 v4, v4
	v_pk_fma_f32 v[46:47], v[2:3], v[2:3], 1.0 op_sel_hi:[1,1,0] neg_lo:[1,0,0] neg_hi:[1,0,0]
	v_exp_f32_e32 v5, v5
	v_max_f32_e32 v1, 0, v46
	v_pk_fma_f32 v[44:45], v[4:5], v[4:5], 1.0 op_sel_hi:[1,1,0] neg_lo:[1,0,0] neg_hi:[1,0,0]
	s_waitcnt vmcnt(27)
	v_lshlrev_b32_e32 v40, 16, v100
	v_and_b32_e32 v41, 0xffff0000, v100
	v_lshlrev_b32_e32 v14, 16, v101
	v_and_b32_e32 v15, 0xffff0000, v101
	s_waitcnt vmcnt(26)
	v_lshlrev_b32_e32 v42, 16, v104
	v_and_b32_e32 v43, 0xffff0000, v104
	v_sqrt_f32_e32 v46, v1
	v_max_f32_e32 v1, 0, v47
	v_lshlrev_b32_e32 v18, 16, v105
	v_and_b32_e32 v19, 0xffff0000, v105
	v_sqrt_f32_e32 v47, v1
	v_max_f32_e32 v1, 0, v44
	v_pk_mul_f32 v[40:41], v[46:47], v[40:41]
	v_sqrt_f32_e32 v44, v1
	v_max_f32_e32 v1, 0, v45
	v_sqrt_f32_e32 v45, v1
	s_nop 0
	v_pk_mul_f32 v[14:15], v[44:45], v[14:15]
	s_nop 0
	v_pk_mul_f32 v[14:15], v[14:15], v[18:19]
	v_pk_mul_f32 v[18:19], v[40:41], v[42:43]
	v_pk_fma_f32 v[4:5], v[62:63], v[4:5], v[14:15]
	v_lshlrev_b32_e32 v14, 16, v98
	v_and_b32_e32 v15, 0xffff0000, v98
	v_pk_mul_f32 v[14:15], v[32:33], v[14:15]
	v_lshlrev_b32_e32 v6, 16, v99
	v_exp_f32_e32 v14, v14
	v_exp_f32_e32 v15, v15
	v_and_b32_e32 v7, 0xffff0000, v99
	v_pk_mul_f32 v[6:7], v[30:31], v[6:7]
	v_exp_f32_e32 v42, v6
	v_pk_fma_f32 v[44:45], v[14:15], v[14:15], 1.0 op_sel_hi:[1,1,0] neg_lo:[1,0,0] neg_hi:[1,0,0]
	v_exp_f32_e32 v43, v7
	v_max_f32_e32 v1, 0, v44
	v_pk_fma_f32 v[6:7], v[42:43], v[42:43], 1.0 op_sel_hi:[1,1,0] neg_lo:[1,0,0] neg_hi:[1,0,0]
	v_pk_fma_f32 v[2:3], v[50:51], v[2:3], v[18:19]
	v_lshlrev_b32_e32 v18, 16, v102
	v_and_b32_e32 v19, 0xffff0000, v102
	v_lshlrev_b32_e32 v16, 16, v103
	v_and_b32_e32 v17, 0xffff0000, v103
	v_lshlrev_b32_e32 v40, 16, v106
	v_sqrt_f32_e32 v44, v1
	v_max_f32_e32 v1, 0, v45
	v_and_b32_e32 v41, 0xffff0000, v106
	v_lshlrev_b32_e32 v20, 16, v107
	v_and_b32_e32 v21, 0xffff0000, v107
	v_sqrt_f32_e32 v45, v1
	v_max_f32_e32 v1, 0, v6
	v_pk_mul_f32 v[18:19], v[44:45], v[18:19]
	v_sqrt_f32_e32 v6, v1
	v_max_f32_e32 v1, 0, v7
	v_sqrt_f32_e32 v7, v1
	s_nop 0
	v_pk_mul_f32 v[6:7], v[6:7], v[16:17]
	s_nop 0
	v_pk_mul_f32 v[16:17], v[6:7], v[20:21]
	v_pk_mul_f32 v[6:7], v[18:19], v[40:41]
	v_pk_fma_f32 v[8:9], v[8:9], v[42:43], v[16:17]
	v_pk_fma_f32 v[6:7], v[64:65], v[14:15], v[6:7]
	s_waitcnt vmcnt(25)
	v_lshlrev_b32_e32 v14, 16, v108
	v_and_b32_e32 v15, 0xffff0000, v108
	v_lshlrev_b32_e32 v16, 16, v109
	v_and_b32_e32 v17, 0xffff0000, v109
	v_pk_mul_f32 v[16:17], v[4:5], v[16:17]
	v_pk_mul_f32 v[14:15], v[2:3], v[14:15]
	v_lshlrev_b32_e32 v18, 16, v111
	v_cvt_pk_bf16_f32 v14, v14, v15
	v_cvt_pk_bf16_f32 v15, v16, v17
	v_lshlrev_b32_e32 v16, 16, v110
	v_and_b32_e32 v17, 0xffff0000, v110
	v_and_b32_e32 v19, 0xffff0000, v111
	v_pk_mul_f32 v[18:19], v[8:9], v[18:19]
	v_pk_mul_f32 v[16:17], v[6:7], v[16:17]
	v_cvt_pk_bf16_f32 v16, v16, v17
	v_cvt_pk_bf16_f32 v17, v18, v19
	global_store_dwordx4 v[212:213], v[14:17], off offset:2048
	s_nop 1
	s_nop 1
	s_nop 1
	s_nop 1
	s_nop 0
	s_waitcnt vmcnt(25)
	v_lshlrev_b32_e32 v70, 16, v112
	v_and_b32_e32 v71, 0xffff0000, v112
	v_pk_mul_f32 v[70:71], v[28:29], v[70:71]
	v_lshlrev_b32_e32 v38, 16, v113
	v_exp_f32_e32 v70, v70
	v_exp_f32_e32 v71, v71
	v_and_b32_e32 v39, 0xffff0000, v113
	v_pk_mul_f32 v[38:39], v[26:27], v[38:39]
	s_nop 0
	v_exp_f32_e32 v38, v38
	v_pk_fma_f32 v[78:79], v[70:71], v[70:71], 1.0 op_sel_hi:[1,1,0] neg_lo:[1,0,0] neg_hi:[1,0,0]
	v_exp_f32_e32 v39, v39
	v_max_f32_e32 v1, 0, v78
	v_pk_fma_f32 v[76:77], v[38:39], v[38:39], 1.0 op_sel_hi:[1,1,0] neg_lo:[1,0,0] neg_hi:[1,0,0]
	s_waitcnt vmcnt(24)
	v_lshlrev_b32_e32 v72, 16, v116
	v_and_b32_e32 v73, 0xffff0000, v116
	v_lshlrev_b32_e32 v42, 16, v117
	v_and_b32_e32 v43, 0xffff0000, v117
	s_waitcnt vmcnt(23)
; __device__ __forceinline__ f32x4 unpack4(u32x2 u) { return (f32x4){__uint_as_float(u.x << 16), __uint_as_float(u.x & 0xffff0000u), __uint_as_float(u.y << 16), __uint_as_float(u.y & 0xffff0000u)}; }
; __device__ __forceinline__ u32x2 pack4(f32x4 v) { u32x2 r; r.x = cvt_pk_bf16(v.x, v.y); r.y = cvt_pk_bf16(v.z, v.w); return r; }
; template <int ph>
; __device__ __forceinline__ void run_phase(const Args& args, LAS unsigned char* lds, const int G, const int bx, const bool fin = true) {
;     ...
;             auto lru_ab = [](f32x4 gr, f32x4 gi, f32x4 xc, f32x4 sp, f32x4& a, f32x4& bb) {
;                 const f32x4 la = gr * sp; a = (f32x4){__expf(la[0]), __expf(la[1]), __expf(la[2]), __expf(la[3])};
;                 const f32x4 om = (f32x4){1.f, 1.f, 1.f, 1.f} - a * a;
;                 bb = (f32x4){sqrtf(fmaxf(om[0], 0.f)), sqrtf(fmaxf(om[1], 0.f)), sqrtf(fmaxf(om[2], 0.f)), sqrtf(fmaxf(om[3], 0.f))} * gi * xc; };
;     ...
; #pragma unroll 8
;                 for (int t = 0; t < 32; ++t) { const size_t o = base + (size_t)t * D;
;                     const u32x4 gr = *(const u32x4*)(GR + o), gi = *(const u32x4*)(GI + o), xc = *(const u32x4*)(XC + o), gg = *(const u32x4*)(GG + o);
;                     f32x4 a, bb;
;                     lru_ab(unpack4((u32x2){gr.x, gr.y}), unpack4((u32x2){gi.x, gi.y}), unpack4((u32x2){xc.x, xc.y}), sp0, a, bb); h0 = a * h0 + bb;
;                     lru_ab(unpack4((u32x2){gr.z, gr.w}), unpack4((u32x2){gi.z, gi.w}), unpack4((u32x2){xc.z, xc.w}), sp1, a, bb); h1 = a * h1 + bb;
;                     const u32x2 w0 = pack4(h0 * unpack4((u32x2){gg.x, gg.y})), w1 = pack4(h1 * unpack4((u32x2){gg.z, gg.w}));
;                     *(u32x4*)(LO + o) = (u32x4){w0.x, w0.y, w1.x, w1.y}; }
	v_lshlrev_b32_e32 v74, 16, v120
	v_sqrt_f32_e32 v78, v1
	v_max_f32_e32 v1, 0, v79
	v_and_b32_e32 v75, 0xffff0000, v120
	v_lshlrev_b32_e32 v46, 16, v121
	v_and_b32_e32 v47, 0xffff0000, v121
	v_sqrt_f32_e32 v79, v1
	v_max_f32_e32 v1, 0, v76
	v_pk_mul_f32 v[72:73], v[78:79], v[72:73]
	v_sqrt_f32_e32 v76, v1
	v_max_f32_e32 v1, 0, v77
	v_sqrt_f32_e32 v77, v1
	s_nop 0
	v_pk_mul_f32 v[42:43], v[76:77], v[42:43]
	s_nop 0
	v_pk_mul_f32 v[42:43], v[42:43], v[46:47]
	v_pk_mul_f32 v[46:47], v[72:73], v[74:75]
	s_nop 0
	v_pk_fma_f32 v[46:47], v[2:3], v[70:71], v[46:47]
	v_lshlrev_b32_e32 v2, 16, v114
	v_and_b32_e32 v3, 0xffff0000, v114
	v_pk_mul_f32 v[2:3], v[32:33], v[2:3]
	v_pk_fma_f32 v[70:71], v[4:5], v[38:39], v[42:43]
	v_exp_f32_e32 v2, v2
	v_exp_f32_e32 v3, v3
	v_lshlrev_b32_e32 v4, 16, v115
	v_and_b32_e32 v5, 0xffff0000, v115
	v_pk_mul_f32 v[4:5], v[30:31], v[4:5]
	v_exp_f32_e32 v4, v4
	v_pk_fma_f32 v[72:73], v[2:3], v[2:3], 1.0 op_sel_hi:[1,1,0] neg_lo:[1,0,0] neg_hi:[1,0,0]
	v_exp_f32_e32 v5, v5
	v_max_f32_e32 v1, 0, v72
	v_lshlrev_b32_e32 v38, 16, v118
	v_and_b32_e32 v39, 0xffff0000, v118
	v_lshlrev_b32_e32 v40, 16, v119
	v_and_b32_e32 v41, 0xffff0000, v119
	v_lshlrev_b32_e32 v42, 16, v122
	v_and_b32_e32 v43, 0xffff0000, v122
	v_lshlrev_b32_e32 v44, 16, v123
	v_and_b32_e32 v45, 0xffff0000, v123
	v_sqrt_f32_e32 v72, v1
	v_max_f32_e32 v1, 0, v73
	v_pk_fma_f32 v[48:49], v[4:5], v[4:5], 1.0 op_sel_hi:[1,1,0] neg_lo:[1,0,0] neg_hi:[1,0,0]
	v_sqrt_f32_e32 v73, v1
	v_max_f32_e32 v1, 0, v48
	v_pk_mul_f32 v[38:39], v[72:73], v[38:39]
	v_pk_mul_f32 v[38:39], v[38:39], v[42:43]
	v_sqrt_f32_e32 v48, v1
	v_max_f32_e32 v1, 0, v49
	v_sqrt_f32_e32 v49, v1
	s_nop 0
	v_pk_mul_f32 v[40:41], v[48:49], v[40:41]
	s_nop 0
	v_pk_mul_f32 v[40:41], v[40:41], v[44:45]
	v_pk_fma_f32 v[44:45], v[6:7], v[2:3], v[38:39]
	v_pk_fma_f32 v[48:49], v[8:9], v[4:5], v[40:41]
	s_waitcnt vmcnt(22)
	v_lshlrev_b32_e32 v2, 16, v124
	v_and_b32_e32 v3, 0xffff0000, v124
	v_lshlrev_b32_e32 v4, 16, v125
	v_and_b32_e32 v5, 0xffff0000, v125
	v_pk_mul_f32 v[4:5], v[70:71], v[4:5]
	v_pk_mul_f32 v[2:3], v[46:47], v[2:3]
	v_lshlrev_b32_e32 v6, 16, v127
	v_cvt_pk_bf16_f32 v2, v2, v3
	v_cvt_pk_bf16_f32 v3, v4, v5
	v_lshlrev_b32_e32 v4, 16, v126
	v_and_b32_e32 v5, 0xffff0000, v126
	v_and_b32_e32 v7, 0xffff0000, v127
	v_pk_mul_f32 v[6:7], v[48:49], v[6:7]
	v_pk_mul_f32 v[4:5], v[44:45], v[4:5]
	s_nop 0
	v_cvt_pk_bf16_f32 v4, v4, v5
	v_cvt_pk_bf16_f32 v5, v6, v7
	global_store_dwordx4 v[224:225], v[2:5], off offset:-4096
	s_nop 0
	s_waitcnt vmcnt(22)
	v_lshlrev_b32_e32 v50, 16, v128
	v_and_b32_e32 v51, 0xffff0000, v128
	v_pk_mul_f32 v[50:51], v[28:29], v[50:51]
	v_lshlrev_b32_e32 v2, 16, v129
	v_exp_f32_e32 v50, v50
	v_exp_f32_e32 v51, v51
	v_and_b32_e32 v3, 0xffff0000, v129
	v_pk_mul_f32 v[2:3], v[26:27], v[2:3]
	v_exp_f32_e32 v2, v2
	v_pk_fma_f32 v[72:73], v[50:51], v[50:51], 1.0 op_sel_hi:[1,1,0] neg_lo:[1,0,0] neg_hi:[1,0,0]
	v_exp_f32_e32 v3, v3
	v_max_f32_e32 v1, 0, v72
	v_pk_fma_f32 v[66:67], v[2:3], v[2:3], 1.0 op_sel_hi:[1,1,0] neg_lo:[1,0,0] neg_hi:[1,0,0]
	s_waitcnt vmcnt(21)
	v_lshlrev_b32_e32 v62, 16, v132
	v_and_b32_e32 v63, 0xffff0000, v132
	v_lshlrev_b32_e32 v6, 16, v133
	v_and_b32_e32 v7, 0xffff0000, v133
	s_waitcnt vmcnt(20)
	v_lshlrev_b32_e32 v64, 16, v136
	v_and_b32_e32 v65, 0xffff0000, v136
	v_sqrt_f32_e32 v72, v1
	v_max_f32_e32 v1, 0, v73
	v_lshlrev_b32_e32 v36, 16, v137
	v_and_b32_e32 v37, 0xffff0000, v137
	v_sqrt_f32_e32 v73, v1
	v_max_f32_e32 v1, 0, v66
	v_pk_mul_f32 v[62:63], v[72:73], v[62:63]
	v_sqrt_f32_e32 v66, v1
	v_max_f32_e32 v1, 0, v67
	v_sqrt_f32_e32 v67, v1
	s_nop 0
	v_pk_mul_f32 v[6:7], v[66:67], v[6:7]
	s_nop 0
	v_pk_mul_f32 v[6:7], v[6:7], v[36:37]
	v_pk_mul_f32 v[36:37], v[62:63], v[64:65]
	s_nop 0
	v_pk_fma_f32 v[46:47], v[46:47], v[50:51], v[36:37]
	v_pk_fma_f32 v[50:51], v[70:71], v[2:3], v[6:7]
	v_lshlrev_b32_e32 v2, 16, v130
	v_and_b32_e32 v3, 0xffff0000, v130
	v_pk_mul_f32 v[2:3], v[32:33], v[2:3]
	v_lshlrev_b32_e32 v4, 16, v131
	v_exp_f32_e32 v2, v2
	v_exp_f32_e32 v3, v3
	v_and_b32_e32 v5, 0xffff0000, v131
	v_pk_mul_f32 v[4:5], v[30:31], v[4:5]
	v_exp_f32_e32 v4, v4
	v_pk_fma_f32 v[64:65], v[2:3], v[2:3], 1.0 op_sel_hi:[1,1,0] neg_lo:[1,0,0] neg_hi:[1,0,0]
	v_exp_f32_e32 v5, v5
	v_max_f32_e32 v1, 0, v64
	v_pk_fma_f32 v[62:63], v[4:5], v[4:5], 1.0 op_sel_hi:[1,1,0] neg_lo:[1,0,0] neg_hi:[1,0,0]
	v_lshlrev_b32_e32 v6, 16, v134
	v_and_b32_e32 v7, 0xffff0000, v134
	v_lshlrev_b32_e32 v8, 16, v135
	v_and_b32_e32 v9, 0xffff0000, v135
	v_lshlrev_b32_e32 v36, 16, v138
	v_and_b32_e32 v37, 0xffff0000, v138
	v_sqrt_f32_e32 v64, v1
	v_max_f32_e32 v1, 0, v65
	v_lshlrev_b32_e32 v38, 16, v139
	v_and_b32_e32 v39, 0xffff0000, v139
	v_sqrt_f32_e32 v65, v1
	v_max_f32_e32 v1, 0, v62
	v_pk_mul_f32 v[6:7], v[64:65], v[6:7]
	v_pk_mul_f32 v[6:7], v[6:7], v[36:37]
	v_pk_fma_f32 v[44:45], v[44:45], v[2:3], v[6:7]
	s_waitcnt vmcnt(19)
	v_lshlrev_b32_e32 v2, 16, v140
	v_and_b32_e32 v3, 0xffff0000, v140
	v_pk_mul_f32 v[2:3], v[46:47], v[2:3]
	v_lshlrev_b32_e32 v6, 16, v143
	v_sqrt_f32_e32 v62, v1
	v_max_f32_e32 v1, 0, v63
	v_cvt_pk_bf16_f32 v2, v2, v3
	v_and_b32_e32 v7, 0xffff0000, v143
	v_sqrt_f32_e32 v63, v1
	s_nop 0
	v_pk_mul_f32 v[8:9], v[62:63], v[8:9]
	s_nop 0
	v_pk_mul_f32 v[8:9], v[8:9], v[38:39]
	s_nop 0
	v_pk_fma_f32 v[48:49], v[48:49], v[4:5], v[8:9]
	v_lshlrev_b32_e32 v4, 16, v141
	v_and_b32_e32 v5, 0xffff0000, v141
	v_pk_mul_f32 v[4:5], v[50:51], v[4:5]
	v_pk_mul_f32 v[6:7], v[48:49], v[6:7]
	v_cvt_pk_bf16_f32 v3, v4, v5
	v_lshlrev_b32_e32 v4, 16, v142
	v_and_b32_e32 v5, 0xffff0000, v142
	v_pk_mul_f32 v[4:5], v[44:45], v[4:5]
	s_nop 0
	v_cvt_pk_bf16_f32 v4, v4, v5
	v_cvt_pk_bf16_f32 v5, v6, v7
	global_store_dwordx4 v[222:223], v[2:5], off offset:2048
	s_nop 0
	s_waitcnt vmcnt(19)
; __device__ __forceinline__ f32x4 unpack4(u32x2 u) { return (f32x4){__uint_as_float(u.x << 16), __uint_as_float(u.x & 0xffff0000u), __uint_as_float(u.y << 16), __uint_as_float(u.y & 0xffff0000u)}; }
; __device__ __forceinline__ u32x2 pack4(f32x4 v) { u32x2 r; r.x = cvt_pk_bf16(v.x, v.y); r.y = cvt_pk_bf16(v.z, v.w); return r; }
; template <int ph>
; __device__ __forceinline__ void run_phase(const Args& args, LAS unsigned char* lds, const int G, const int bx, const bool fin = true) {
;     ...
;             auto lru_ab = [](f32x4 gr, f32x4 gi, f32x4 xc, f32x4 sp, f32x4& a, f32x4& bb) {
;                 const f32x4 la = gr * sp; a = (f32x4){__expf(la[0]), __expf(la[1]), __expf(la[2]), __expf(la[3])};
;                 const f32x4 om = (f32x4){1.f, 1.f, 1.f, 1.f} - a * a;
;                 bb = (f32x4){sqrtf(fmaxf(om[0], 0.f)), sqrtf(fmaxf(om[1], 0.f)), sqrtf(fmaxf(om[2], 0.f)), sqrtf(fmaxf(om[3], 0.f))} * gi * xc; };
;     ...
; #pragma unroll 8
;                 for (int t = 0; t < 32; ++t) { const size_t o = base + (size_t)t * D;
;                     const u32x4 gr = *(const u32x4*)(GR + o), gi = *(const u32x4*)(GI + o), xc = *(const u32x4*)(XC + o), gg = *(const u32x4*)(GG + o);
;                     f32x4 a, bb;
;                     lru_ab(unpack4((u32x2){gr.x, gr.y}), unpack4((u32x2){gi.x, gi.y}), unpack4((u32x2){xc.x, xc.y}), sp0, a, bb); h0 = a * h0 + bb;
;                     lru_ab(unpack4((u32x2){gr.z, gr.w}), unpack4((u32x2){gi.z, gi.w}), unpack4((u32x2){xc.z, xc.w}), sp1, a, bb); h1 = a * h1 + bb;
;                     const u32x2 w0 = pack4(h0 * unpack4((u32x2){gg.x, gg.y})), w1 = pack4(h1 * unpack4((u32x2){gg.z, gg.w}));
;                     *(u32x4*)(LO + o) = (u32x4){w0.x, w0.y, w1.x, w1.y}; }
	v_lshlrev_b32_e32 v20, 16, v144
	v_and_b32_e32 v21, 0xffff0000, v144
	v_pk_mul_f32 v[20:21], v[28:29], v[20:21]
	v_lshlrev_b32_e32 v2, 16, v145
	v_exp_f32_e32 v20, v20
	v_exp_f32_e32 v21, v21
	v_and_b32_e32 v3, 0xffff0000, v145
	v_pk_mul_f32 v[2:3], v[26:27], v[2:3]
	v_exp_f32_e32 v2, v2
	v_pk_fma_f32 v[70:71], v[20:21], v[20:21], 1.0 op_sel_hi:[1,1,0] neg_lo:[1,0,0] neg_hi:[1,0,0]
	v_exp_f32_e32 v3, v3
	v_max_f32_e32 v1, 0, v70
	v_pk_fma_f32 v[66:67], v[2:3], v[2:3], 1.0 op_sel_hi:[1,1,0] neg_lo:[1,0,0] neg_hi:[1,0,0]
	s_waitcnt vmcnt(18)
	v_lshlrev_b32_e32 v62, 16, v148
	v_and_b32_e32 v63, 0xffff0000, v148
	v_lshlrev_b32_e32 v6, 16, v149
	v_and_b32_e32 v7, 0xffff0000, v149
	s_waitcnt vmcnt(17)
	v_lshlrev_b32_e32 v64, 16, v152
	v_and_b32_e32 v65, 0xffff0000, v152
	v_sqrt_f32_e32 v70, v1
	v_max_f32_e32 v1, 0, v71
	v_lshlrev_b32_e32 v36, 16, v153
	v_and_b32_e32 v37, 0xffff0000, v153
	v_sqrt_f32_e32 v71, v1
	v_max_f32_e32 v1, 0, v66
	v_pk_mul_f32 v[62:63], v[70:71], v[62:63]
	v_sqrt_f32_e32 v66, v1
	v_max_f32_e32 v1, 0, v67
	v_sqrt_f32_e32 v67, v1
	s_nop 0
	v_pk_mul_f32 v[6:7], v[66:67], v[6:7]
	s_nop 0
	v_pk_mul_f32 v[6:7], v[6:7], v[36:37]
	v_pk_mul_f32 v[36:37], v[62:63], v[64:65]
	v_pk_fma_f32 v[50:51], v[50:51], v[2:3], v[6:7]
	v_lshlrev_b32_e32 v2, 16, v146
	v_and_b32_e32 v3, 0xffff0000, v146
	v_pk_mul_f32 v[2:3], v[32:33], v[2:3]
	v_lshlrev_b32_e32 v4, 16, v147
	v_exp_f32_e32 v2, v2
	v_exp_f32_e32 v3, v3
	v_and_b32_e32 v5, 0xffff0000, v147
	v_pk_mul_f32 v[4:5], v[30:31], v[4:5]
	v_exp_f32_e32 v4, v4
	v_pk_fma_f32 v[62:63], v[2:3], v[2:3], 1.0 op_sel_hi:[1,1,0] neg_lo:[1,0,0] neg_hi:[1,0,0]
	v_exp_f32_e32 v5, v5
	v_max_f32_e32 v1, 0, v62
	v_pk_fma_f32 v[46:47], v[46:47], v[20:21], v[36:37]
	v_lshlrev_b32_e32 v20, 16, v154
	v_and_b32_e32 v21, 0xffff0000, v154
	v_lshlrev_b32_e32 v36, 16, v155
	v_and_b32_e32 v37, 0xffff0000, v155
	v_pk_fma_f32 v[38:39], v[4:5], v[4:5], 1.0 op_sel_hi:[1,1,0] neg_lo:[1,0,0] neg_hi:[1,0,0]
	v_lshlrev_b32_e32 v6, 16, v150
	v_sqrt_f32_e32 v62, v1
	v_max_f32_e32 v1, 0, v63
	v_and_b32_e32 v7, 0xffff0000, v150
	v_lshlrev_b32_e32 v8, 16, v151
	v_and_b32_e32 v9, 0xffff0000, v151
	v_sqrt_f32_e32 v63, v1
	v_max_f32_e32 v1, 0, v38
	v_pk_mul_f32 v[6:7], v[62:63], v[6:7]
	v_pk_mul_f32 v[6:7], v[6:7], v[20:21]
	v_pk_fma_f32 v[44:45], v[44:45], v[2:3], v[6:7]
	s_waitcnt vmcnt(16)
	v_lshlrev_b32_e32 v2, 16, v156
	v_and_b32_e32 v3, 0xffff0000, v156
	v_pk_mul_f32 v[2:3], v[46:47], v[2:3]
	v_lshlrev_b32_e32 v6, 16, v159
	v_sqrt_f32_e32 v38, v1
	v_max_f32_e32 v1, 0, v39
	v_cvt_pk_bf16_f32 v2, v2, v3
	v_and_b32_e32 v7, 0xffff0000, v159
	v_sqrt_f32_e32 v39, v1
	s_nop 0
	v_pk_mul_f32 v[8:9], v[38:39], v[8:9]
	s_nop 0
	v_pk_mul_f32 v[8:9], v[8:9], v[36:37]
	s_nop 0
	v_pk_fma_f32 v[8:9], v[48:49], v[4:5], v[8:9]
	v_lshlrev_b32_e32 v4, 16, v157
	v_and_b32_e32 v5, 0xffff0000, v157
	v_pk_mul_f32 v[4:5], v[50:51], v[4:5]
	v_pk_mul_f32 v[6:7], v[8:9], v[6:7]
	v_cvt_pk_bf16_f32 v3, v4, v5
	v_lshlrev_b32_e32 v4, 16, v158
	v_and_b32_e32 v5, 0xffff0000, v158
	v_pk_mul_f32 v[4:5], v[44:45], v[4:5]
	s_nop 0
	v_cvt_pk_bf16_f32 v4, v4, v5
	v_cvt_pk_bf16_f32 v5, v6, v7
	global_store_dwordx4 v[224:225], v[2:5], off
	s_nop 0
	s_nop 0
	s_nop 0
	s_waitcnt vmcnt(16)
	v_lshlrev_b32_e32 v2, 16, v160
	v_and_b32_e32 v3, 0xffff0000, v160
	v_pk_mul_f32 v[2:3], v[28:29], v[2:3]
	v_lshlrev_b32_e32 v4, 16, v161
	v_exp_f32_e32 v2, v2
	v_exp_f32_e32 v3, v3
	v_and_b32_e32 v5, 0xffff0000, v161
	v_pk_mul_f32 v[4:5], v[26:27], v[4:5]
	v_exp_f32_e32 v4, v4
	v_pk_fma_f32 v[62:63], v[2:3], v[2:3], 1.0 op_sel_hi:[1,1,0] neg_lo:[1,0,0] neg_hi:[1,0,0]
	v_exp_f32_e32 v5, v5
	v_max_f32_e32 v1, 0, v62
	v_pk_fma_f32 v[48:49], v[4:5], v[4:5], 1.0 op_sel_hi:[1,1,0] neg_lo:[1,0,0] neg_hi:[1,0,0]
	s_waitcnt vmcnt(15)
	v_lshlrev_b32_e32 v40, 16, v164
	v_and_b32_e32 v41, 0xffff0000, v164
	v_lshlrev_b32_e32 v36, 16, v165
	v_and_b32_e32 v37, 0xffff0000, v165
	s_waitcnt vmcnt(14)
	v_lshlrev_b32_e32 v42, 16, v168
	v_and_b32_e32 v43, 0xffff0000, v168
	v_sqrt_f32_e32 v62, v1
	v_max_f32_e32 v1, 0, v63
	v_lshlrev_b32_e32 v14, 16, v169
	v_and_b32_e32 v15, 0xffff0000, v169
	v_sqrt_f32_e32 v63, v1
	v_max_f32_e32 v1, 0, v48
	v_pk_mul_f32 v[40:41], v[62:63], v[40:41]
	v_sqrt_f32_e32 v48, v1
	v_max_f32_e32 v1, 0, v49
	v_sqrt_f32_e32 v49, v1
	s_nop 0
	v_pk_mul_f32 v[36:37], v[48:49], v[36:37]
	s_nop 0
	v_pk_mul_f32 v[14:15], v[36:37], v[14:15]
	v_pk_mul_f32 v[36:37], v[40:41], v[42:43]
	v_pk_fma_f32 v[4:5], v[50:51], v[4:5], v[14:15]
	v_lshlrev_b32_e32 v14, 16, v162
	v_and_b32_e32 v15, 0xffff0000, v162
	v_pk_mul_f32 v[14:15], v[32:33], v[14:15]
	v_lshlrev_b32_e32 v6, 16, v163
	v_exp_f32_e32 v14, v14
	v_exp_f32_e32 v15, v15
	v_and_b32_e32 v7, 0xffff0000, v163
	v_pk_mul_f32 v[6:7], v[30:31], v[6:7]
	v_pk_fma_f32 v[2:3], v[46:47], v[2:3], v[36:37]
	v_exp_f32_e32 v42, v6
	v_pk_fma_f32 v[46:47], v[14:15], v[14:15], 1.0 op_sel_hi:[1,1,0] neg_lo:[1,0,0] neg_hi:[1,0,0]
	v_exp_f32_e32 v43, v7
	v_max_f32_e32 v1, 0, v46
	v_pk_fma_f32 v[6:7], v[42:43], v[42:43], 1.0 op_sel_hi:[1,1,0] neg_lo:[1,0,0] neg_hi:[1,0,0]
	v_lshlrev_b32_e32 v36, 16, v166
	v_and_b32_e32 v37, 0xffff0000, v166
	v_lshlrev_b32_e32 v38, 16, v167
	v_and_b32_e32 v39, 0xffff0000, v167
	v_lshlrev_b32_e32 v40, 16, v170
	v_and_b32_e32 v41, 0xffff0000, v170
	v_sqrt_f32_e32 v46, v1
	v_max_f32_e32 v1, 0, v47
	v_lshlrev_b32_e32 v16, 16, v171
	v_and_b32_e32 v17, 0xffff0000, v171
	v_sqrt_f32_e32 v47, v1
	v_max_f32_e32 v1, 0, v6
	v_pk_mul_f32 v[36:37], v[46:47], v[36:37]
	v_sqrt_f32_e32 v6, v1
	v_max_f32_e32 v1, 0, v7
	v_sqrt_f32_e32 v7, v1
	s_nop 0
	v_pk_mul_f32 v[6:7], v[6:7], v[38:39]
	s_nop 0
	v_pk_mul_f32 v[16:17], v[6:7], v[16:17]
	v_pk_mul_f32 v[6:7], v[36:37], v[40:41]
	v_pk_fma_f32 v[8:9], v[8:9], v[42:43], v[16:17]
	v_pk_fma_f32 v[6:7], v[44:45], v[14:15], v[6:7]
	s_waitcnt vmcnt(13)
; __device__ __forceinline__ f32x4 unpack4(u32x2 u) { return (f32x4){__uint_as_float(u.x << 16), __uint_as_float(u.x & 0xffff0000u), __uint_as_float(u.y << 16), __uint_as_float(u.y & 0xffff0000u)}; }
; __device__ __forceinline__ u32x2 pack4(f32x4 v) { u32x2 r; r.x = cvt_pk_bf16(v.x, v.y); r.y = cvt_pk_bf16(v.z, v.w); return r; }
; template <int ph>
; __device__ __forceinline__ void run_phase(const Args& args, LAS unsigned char* lds, const int G, const int bx, const bool fin = true) {
;     ...
;             auto lru_ab = [](f32x4 gr, f32x4 gi, f32x4 xc, f32x4 sp, f32x4& a, f32x4& bb) {
;                 const f32x4 la = gr * sp; a = (f32x4){__expf(la[0]), __expf(la[1]), __expf(la[2]), __expf(la[3])};
;                 const f32x4 om = (f32x4){1.f, 1.f, 1.f, 1.f} - a * a;
;                 bb = (f32x4){sqrtf(fmaxf(om[0], 0.f)), sqrtf(fmaxf(om[1], 0.f)), sqrtf(fmaxf(om[2], 0.f)), sqrtf(fmaxf(om[3], 0.f))} * gi * xc; };
;     ...
; #pragma unroll 8
;                 for (int t = 0; t < 32; ++t) { const size_t o = base + (size_t)t * D;
;                     const u32x4 gr = *(const u32x4*)(GR + o), gi = *(const u32x4*)(GI + o), xc = *(const u32x4*)(XC + o), gg = *(const u32x4*)(GG + o);
;                     f32x4 a, bb;
;                     lru_ab(unpack4((u32x2){gr.x, gr.y}), unpack4((u32x2){gi.x, gi.y}), unpack4((u32x2){xc.x, xc.y}), sp0, a, bb); h0 = a * h0 + bb;
;                     lru_ab(unpack4((u32x2){gr.z, gr.w}), unpack4((u32x2){gi.z, gi.w}), unpack4((u32x2){xc.z, xc.w}), sp1, a, bb); h1 = a * h1 + bb;
;                     const u32x2 w0 = pack4(h0 * unpack4((u32x2){gg.x, gg.y})), w1 = pack4(h1 * unpack4((u32x2){gg.z, gg.w}));
;                     *(u32x4*)(LO + o) = (u32x4){w0.x, w0.y, w1.x, w1.y}; }
	v_lshlrev_b32_e32 v14, 16, v172
	v_and_b32_e32 v15, 0xffff0000, v172
	v_lshlrev_b32_e32 v16, 16, v173
	v_and_b32_e32 v17, 0xffff0000, v173
	v_pk_mul_f32 v[16:17], v[4:5], v[16:17]
	v_pk_mul_f32 v[14:15], v[2:3], v[14:15]
	v_lshlrev_b32_e32 v18, 16, v175
	v_cvt_pk_bf16_f32 v14, v14, v15
	v_cvt_pk_bf16_f32 v15, v16, v17
	v_lshlrev_b32_e32 v16, 16, v174
	v_and_b32_e32 v17, 0xffff0000, v174
	v_and_b32_e32 v19, 0xffff0000, v175
	v_pk_mul_f32 v[18:19], v[8:9], v[18:19]
	v_pk_mul_f32 v[16:17], v[6:7], v[16:17]
	s_nop 0
	v_cvt_pk_bf16_f32 v16, v16, v17
	v_cvt_pk_bf16_f32 v17, v18, v19
	global_store_dwordx4 v[224:225], v[14:17], off offset:2048
	s_nop 1
	s_nop 1
	s_nop 0
	s_waitcnt vmcnt(12)
	v_lshlrev_b32_e32 v40, 16, v180
	v_lshlrev_b32_e32 v38, 16, v176
	v_and_b32_e32 v39, 0xffff0000, v176
	v_pk_mul_f32 v[38:39], v[28:29], v[38:39]
	v_lshlrev_b32_e32 v14, 16, v177
	v_exp_f32_e32 v38, v38
	v_exp_f32_e32 v39, v39
	v_and_b32_e32 v15, 0xffff0000, v177
	v_pk_mul_f32 v[14:15], v[26:27], v[14:15]
	v_exp_f32_e32 v14, v14
	v_pk_fma_f32 v[66:67], v[38:39], v[38:39], 1.0 op_sel_hi:[1,1,0] neg_lo:[1,0,0] neg_hi:[1,0,0]
	v_exp_f32_e32 v15, v15
	v_max_f32_e32 v1, 0, v66
	v_pk_fma_f32 v[64:65], v[14:15], v[14:15], 1.0 op_sel_hi:[1,1,0] neg_lo:[1,0,0] neg_hi:[1,0,0]
	v_and_b32_e32 v41, 0xffff0000, v180
	v_lshlrev_b32_e32 v18, 16, v181
	v_and_b32_e32 v19, 0xffff0000, v181
	s_waitcnt vmcnt(11)
	v_lshlrev_b32_e32 v62, 16, v184
	v_and_b32_e32 v63, 0xffff0000, v184
	v_lshlrev_b32_e32 v44, 16, v185
	v_sqrt_f32_e32 v66, v1
	v_max_f32_e32 v1, 0, v67
	v_and_b32_e32 v45, 0xffff0000, v185
	v_sqrt_f32_e32 v67, v1
	v_max_f32_e32 v1, 0, v64
	v_pk_mul_f32 v[40:41], v[66:67], v[40:41]
	v_pk_mul_f32 v[40:41], v[40:41], v[62:63]
	v_pk_fma_f32 v[2:3], v[2:3], v[38:39], v[40:41]
	v_lshlrev_b32_e32 v38, 16, v187
	v_and_b32_e32 v39, 0xffff0000, v187
	v_sqrt_f32_e32 v64, v1
	v_max_f32_e32 v1, 0, v65
	v_sqrt_f32_e32 v65, v1
	s_nop 0
	v_pk_mul_f32 v[18:19], v[64:65], v[18:19]
	s_nop 0
	v_pk_mul_f32 v[18:19], v[18:19], v[44:45]
	s_nop 0
	v_pk_fma_f32 v[40:41], v[4:5], v[14:15], v[18:19]
	v_lshlrev_b32_e32 v4, 16, v178
	v_and_b32_e32 v5, 0xffff0000, v178
	v_pk_mul_f32 v[4:5], v[32:33], v[4:5]
	v_lshlrev_b32_e32 v14, 16, v179
	v_exp_f32_e32 v4, v4
	v_exp_f32_e32 v5, v5
	v_and_b32_e32 v15, 0xffff0000, v179
	v_pk_mul_f32 v[14:15], v[30:31], v[14:15]
	v_lshlrev_b32_e32 v16, 16, v182
	v_and_b32_e32 v17, 0xffff0000, v182
	v_lshlrev_b32_e32 v18, 16, v183
	v_and_b32_e32 v19, 0xffff0000, v183
	v_lshlrev_b32_e32 v20, 16, v186
	v_and_b32_e32 v21, 0xffff0000, v186
	v_exp_f32_e32 v14, v14
	v_pk_fma_f32 v[46:47], v[4:5], v[4:5], 1.0 op_sel_hi:[1,1,0] neg_lo:[1,0,0] neg_hi:[1,0,0]
	v_exp_f32_e32 v15, v15
	v_max_f32_e32 v1, 0, v46
	v_pk_fma_f32 v[44:45], v[14:15], v[14:15], 1.0 op_sel_hi:[1,1,0] neg_lo:[1,0,0] neg_hi:[1,0,0]
	v_sqrt_f32_e32 v46, v1
	v_max_f32_e32 v1, 0, v47
	v_sqrt_f32_e32 v47, v1
	v_max_f32_e32 v1, 0, v44
	v_pk_mul_f32 v[16:17], v[46:47], v[16:17]
	v_pk_mul_f32 v[16:17], v[16:17], v[20:21]
	v_sqrt_f32_e32 v44, v1
	v_max_f32_e32 v1, 0, v45
	v_sqrt_f32_e32 v45, v1
	s_nop 0
	v_pk_mul_f32 v[18:19], v[44:45], v[18:19]
	s_nop 0
	v_pk_mul_f32 v[18:19], v[18:19], v[38:39]
	v_pk_fma_f32 v[38:39], v[6:7], v[4:5], v[16:17]
	s_waitcnt vmcnt(10)
	v_lshlrev_b32_e32 v4, 16, v188
	v_and_b32_e32 v5, 0xffff0000, v188
	v_lshlrev_b32_e32 v6, 16, v189
	v_and_b32_e32 v7, 0xffff0000, v189
	v_pk_mul_f32 v[6:7], v[40:41], v[6:7]
	v_pk_mul_f32 v[4:5], v[2:3], v[4:5]
	v_pk_fma_f32 v[8:9], v[8:9], v[14:15], v[18:19]
	v_cvt_pk_bf16_f32 v4, v4, v5
	v_cvt_pk_bf16_f32 v5, v6, v7
	v_lshlrev_b32_e32 v6, 16, v190
	v_and_b32_e32 v7, 0xffff0000, v190
	v_lshlrev_b32_e32 v14, 16, v191
	v_and_b32_e32 v15, 0xffff0000, v191
	v_pk_mul_f32 v[14:15], v[8:9], v[14:15]
	v_pk_mul_f32 v[6:7], v[38:39], v[6:7]
	s_nop 0
	v_cvt_pk_bf16_f32 v6, v6, v7
	v_cvt_pk_bf16_f32 v7, v14, v15
	global_store_dwordx4 v[238:239], v[4:7], off
	s_nop 0
	s_nop 0
	s_waitcnt vmcnt(10)
; __device__ __forceinline__ f32x4 unpack4(u32x2 u) { return (f32x4){__uint_as_float(u.x << 16), __uint_as_float(u.x & 0xffff0000u), __uint_as_float(u.y << 16), __uint_as_float(u.y & 0xffff0000u)}; }
; __device__ __forceinline__ u32x2 pack4(f32x4 v) { u32x2 r; r.x = cvt_pk_bf16(v.x, v.y); r.y = cvt_pk_bf16(v.z, v.w); return r; }
; template <int ph>
; __device__ __forceinline__ void run_phase(const Args& args, LAS unsigned char* lds, const int G, const int bx, const bool fin = true) {
;     ...
;             auto lru_ab = [](f32x4 gr, f32x4 gi, f32x4 xc, f32x4 sp, f32x4& a, f32x4& bb) {
;                 const f32x4 la = gr * sp; a = (f32x4){__expf(la[0]), __expf(la[1]), __expf(la[2]), __expf(la[3])};
;                 const f32x4 om = (f32x4){1.f, 1.f, 1.f, 1.f} - a * a;
;                 bb = (f32x4){sqrtf(fmaxf(om[0], 0.f)), sqrtf(fmaxf(om[1], 0.f)), sqrtf(fmaxf(om[2], 0.f)), sqrtf(fmaxf(om[3], 0.f))} * gi * xc; };
;     ...
; #pragma unroll 8
;                 for (int t = 0; t < 32; ++t) { const size_t o = base + (size_t)t * D;
;                     const u32x4 gr = *(const u32x4*)(GR + o), gi = *(const u32x4*)(GI + o), xc = *(const u32x4*)(XC + o), gg = *(const u32x4*)(GG + o);
;                     f32x4 a, bb;
;                     lru_ab(unpack4((u32x2){gr.x, gr.y}), unpack4((u32x2){gi.x, gi.y}), unpack4((u32x2){xc.x, xc.y}), sp0, a, bb); h0 = a * h0 + bb;
;                     lru_ab(unpack4((u32x2){gr.z, gr.w}), unpack4((u32x2){gi.z, gi.w}), unpack4((u32x2){xc.z, xc.w}), sp1, a, bb); h1 = a * h1 + bb;
;                     const u32x2 w0 = pack4(h0 * unpack4((u32x2){gg.x, gg.y})), w1 = pack4(h1 * unpack4((u32x2){gg.z, gg.w}));
;                     *(u32x4*)(LO + o) = (u32x4){w0.x, w0.y, w1.x, w1.y}; }
;                 if (seg == 63) { *(f32x4*)(out + O_PLRU + (size_t)b * D + ch) = h0; *(f32x4*)(out + O_PLRU + (size_t)b * D + ch + 4) = h1; }
	v_lshlrev_b32_e32 v42, 16, v192
	v_and_b32_e32 v43, 0xffff0000, v192
	v_pk_mul_f32 v[42:43], v[28:29], v[42:43]
	v_lshlrev_b32_e32 v18, 16, v193
	v_exp_f32_e32 v42, v42
	v_exp_f32_e32 v43, v43
	v_and_b32_e32 v19, 0xffff0000, v193
	v_pk_mul_f32 v[18:19], v[26:27], v[18:19]
	v_exp_f32_e32 v18, v18
	v_pk_fma_f32 v[50:51], v[42:43], v[42:43], 1.0 op_sel_hi:[1,1,0] neg_lo:[1,0,0] neg_hi:[1,0,0]
	v_exp_f32_e32 v19, v19
	v_max_f32_e32 v1, 0, v50
	v_pk_fma_f32 v[48:49], v[18:19], v[18:19], 1.0 op_sel_hi:[1,1,0] neg_lo:[1,0,0] neg_hi:[1,0,0]
	s_waitcnt vmcnt(9)
	v_lshlrev_b32_e32 v44, 16, v196
	v_and_b32_e32 v45, 0xffff0000, v196
	v_lshlrev_b32_e32 v14, 16, v197
	v_and_b32_e32 v15, 0xffff0000, v197
	s_waitcnt vmcnt(8)
	v_lshlrev_b32_e32 v46, 16, v204
	v_and_b32_e32 v47, 0xffff0000, v204
	v_sqrt_f32_e32 v50, v1
	v_max_f32_e32 v1, 0, v51
	v_lshlrev_b32_e32 v4, 16, v205
	v_and_b32_e32 v5, 0xffff0000, v205
	v_sqrt_f32_e32 v51, v1
	v_max_f32_e32 v1, 0, v48
	v_pk_mul_f32 v[44:45], v[50:51], v[44:45]
	v_pk_mul_f32 v[44:45], v[44:45], v[46:47]
	v_pk_fma_f32 v[2:3], v[2:3], v[42:43], v[44:45]
	v_sqrt_f32_e32 v48, v1
	v_max_f32_e32 v1, 0, v49
	v_sqrt_f32_e32 v49, v1
	s_nop 0
	v_pk_mul_f32 v[14:15], v[48:49], v[14:15]
	s_nop 0
	v_pk_mul_f32 v[4:5], v[14:15], v[4:5]
	v_lshlrev_b32_e32 v14, 16, v194
	v_and_b32_e32 v15, 0xffff0000, v194
	v_pk_mul_f32 v[14:15], v[32:33], v[14:15]
	v_pk_fma_f32 v[4:5], v[40:41], v[18:19], v[4:5]
	v_exp_f32_e32 v14, v14
	v_exp_f32_e32 v15, v15
	v_lshlrev_b32_e32 v18, 16, v195
	v_and_b32_e32 v19, 0xffff0000, v195
	v_pk_mul_f32 v[18:19], v[30:31], v[18:19]
	v_exp_f32_e32 v18, v18
	v_pk_fma_f32 v[44:45], v[14:15], v[14:15], 1.0 op_sel_hi:[1,1,0] neg_lo:[1,0,0] neg_hi:[1,0,0]
	v_exp_f32_e32 v19, v19
	v_max_f32_e32 v1, 0, v44
	v_pk_fma_f32 v[42:43], v[18:19], v[18:19], 1.0 op_sel_hi:[1,1,0] neg_lo:[1,0,0] neg_hi:[1,0,0]
	v_lshlrev_b32_e32 v20, 16, v198
	v_and_b32_e32 v21, 0xffff0000, v198
	v_lshlrev_b32_e32 v16, 16, v199
	v_and_b32_e32 v17, 0xffff0000, v199
	v_lshlrev_b32_e32 v40, 16, v206
	v_and_b32_e32 v41, 0xffff0000, v206
	v_sqrt_f32_e32 v44, v1
	v_max_f32_e32 v1, 0, v45
	v_lshlrev_b32_e32 v6, 16, v207
	v_and_b32_e32 v7, 0xffff0000, v207
	v_sqrt_f32_e32 v45, v1
	v_max_f32_e32 v1, 0, v42
	v_pk_mul_f32 v[20:21], v[44:45], v[20:21]
	v_pk_mul_f32 v[20:21], v[20:21], v[40:41]
	v_sqrt_f32_e32 v42, v1
	v_max_f32_e32 v1, 0, v43
	v_sqrt_f32_e32 v43, v1
	s_nop 0
	v_pk_mul_f32 v[16:17], v[42:43], v[16:17]
	s_nop 0
	v_pk_mul_f32 v[6:7], v[16:17], v[6:7]
	s_nop 0
	v_pk_fma_f32 v[8:9], v[8:9], v[18:19], v[6:7]
	v_pk_fma_f32 v[6:7], v[38:39], v[14:15], v[20:21]
	s_waitcnt vmcnt(7)
	v_lshlrev_b32_e32 v14, 16, v208
	v_and_b32_e32 v15, 0xffff0000, v208
	v_lshlrev_b32_e32 v10, 16, v209
	v_and_b32_e32 v11, 0xffff0000, v209
	v_pk_mul_f32 v[16:17], v[4:5], v[10:11]
	v_pk_mul_f32 v[10:11], v[2:3], v[14:15]
	v_lshlrev_b32_e32 v14, 16, v210
	v_and_b32_e32 v15, 0xffff0000, v210
	v_lshlrev_b32_e32 v12, 16, v211
	v_and_b32_e32 v13, 0xffff0000, v211
	v_cvt_pk_bf16_f32 v10, v10, v11
	v_cvt_pk_bf16_f32 v11, v16, v17
	v_pk_mul_f32 v[16:17], v[8:9], v[12:13]
	v_pk_mul_f32 v[12:13], v[6:7], v[14:15]
	s_nop 0
	v_cvt_pk_bf16_f32 v12, v12, v13
	v_cvt_pk_bf16_f32 v13, v16, v17
	global_store_dwordx4 v[238:239], v[10:13], off offset:2048
	s_cbranch_scc0 .LBB0_1073
	s_and_saveexec_b64 s[0:1], s[4:5]
	s_cbranch_execz .LBB0_1043
	s_lshl_b64 s[10:11], s[22:23], 12
	s_add_u32 s10, s59, s10
	s_addc_u32 s11, s60, s11
	global_store_dwordx4 v60, v[2:5], s[10:11]
	global_store_dwordx4 v60, v[6:9], s[10:11] offset:16
	s_branch .LBB0_1043
